# route q-GEMM: 2-deep register prefetch (K-loop unrolled x2 + peeled last iteration, key-tile loads moved into the peeled iteration)
# baseline (speedup 1.0000x reference)
.LBB0_1003:
	s_xor_b64 s[56:57], s[58:59], -1
	s_lshl_b32 s58, s80, 3
	s_or_b32 s58, s38, s58
	s_mov_b32 s59, s39
	s_lshl_b64 s[58:59], s[58:59], 15
	s_mov_b64 s[98:99], s[58:59]
	v_mov_b32_e32 v48, v133
	s_lshl_b32 s58, s80, 18
	s_add_u32 s58, s2, s58
	v_add_u32_e32 v8, 0x100, v48
	v_add_u32_e32 v16, 0x200, v48
	v_add_u32_e32 v28, 0x300, v48
	v_lshlrev_b32_e32 v0, 4, v48
	v_ashrrev_i32_e32 v32, 3, v48
	v_ashrrev_i32_e32 v36, 3, v8
	v_ashrrev_i32_e32 v40, 3, v16
	v_ashrrev_i32_e32 v44, 3, v28
	s_addc_u32 s59, s3, 0
	v_and_b32_e32 v128, 0x70, v0
	v_ashrrev_i32_e32 v33, 31, v32
	v_ashrrev_i32_e32 v37, 31, v36
	v_ashrrev_i32_e32 v41, 31, v40
	v_ashrrev_i32_e32 v45, 31, v44
	v_lshl_add_u64 v[24:25], s[58:59], 0, v[128:129]
	v_lshl_add_u64 v[26:27], s[50:51], 0, v[128:129]
	v_lshlrev_b64 v[34:35], 11, v[32:33]
	v_lshlrev_b64 v[38:39], 11, v[36:37]
	v_lshlrev_b64 v[42:43], 11, v[40:41]
	v_lshlrev_b64 v[46:47], 11, v[44:45]
	v_lshl_add_u64 v[0:1], v[24:25], 0, v[34:35]
	v_lshl_add_u64 v[4:5], v[26:27], 0, v[34:35]
	v_lshl_add_u64 v[8:9], v[24:25], 0, v[38:39]
	v_lshl_add_u64 v[12:13], v[26:27], 0, v[38:39]
	v_lshl_add_u64 v[16:17], v[24:25], 0, v[42:43]
	v_lshl_add_u64 v[20:21], v[26:27], 0, v[42:43]
	v_lshl_add_u64 v[24:25], v[24:25], 0, v[46:47]
	v_lshl_add_u64 v[28:29], v[26:27], 0, v[46:47]
	global_load_dwordx4 v[0:3], v[0:1], off
	s_nop 0
	global_load_dwordx4 v[4:7], v[4:5], off
	s_nop 0
	global_load_dwordx4 v[8:11], v[8:9], off
	s_nop 0
	global_load_dwordx4 v[12:15], v[12:13], off
	s_nop 0
	global_load_dwordx4 v[16:19], v[16:17], off
	s_nop 0
	global_load_dwordx4 v[20:23], v[20:21], off
	s_nop 0
	global_load_dwordx4 v[24:27], v[24:25], off
	s_nop 0
	global_load_dwordx4 v[28:31], v[28:29], off
	v_mul_lo_u32 v233, v32, s85
	s_lshl_b64 s[58:59], s[80:81], 18
	v_add_u32_e32 v41, v128, v233
	v_mul_lo_u32 v235, v36, s85
	v_mul_lo_u32 v236, v40, s85
	v_mul_lo_u32 v237, v44, s85
	v_add_u32_e32 v40, v128, v235
	v_add_u32_e32 v44, v128, v236
	v_add_u32_e32 v45, v128, v237
	v_and_b32_e32 v33, 31, v48
	v_lshrrev_b32_e32 v37, 1, v48
	v_or_b32_e32 v32, v33, v192
	v_mul_u32_u24_e32 v232, 0x90, v33
	v_and_b32_e32 v231, 16, v37
	v_mul_lo_u32 v234, v32, s85
	v_lshl_add_u64 v[32:33], s[58:59], 0, v[34:35]
	v_lshl_add_u64 v[36:37], s[58:59], 0, v[38:39]
	v_or_b32_e32 v32, v32, v128
	v_or_b32_e32 v36, v36, v128
	v_or_b32_e32 v34, v34, v128
	v_or_b32_e32 v38, v38, v128
	v_lshl_add_u64 v[160:161], s[52:53], 0, v[32:33]
	v_lshl_add_u64 v[162:163], s[52:53], 0, v[36:37]
	v_lshl_add_u64 v[168:169], s[54:55], 0, v[34:35]
	v_lshl_add_u64 v[170:171], s[54:55], 0, v[38:39]
	s_mov_b32 s76, 0
	s_waitcnt vmcnt(7)
	ds_write_b128 v41, v[0:3]
	s_waitcnt vmcnt(6)
	ds_write_b128 v41, v[4:7] offset:36864
	s_waitcnt vmcnt(5)
	ds_write_b128 v40, v[8:11]
	s_waitcnt vmcnt(4)
	ds_write_b128 v40, v[12:15] offset:36864
	s_waitcnt vmcnt(3)
	ds_write_b128 v44, v[16:19]
	s_waitcnt vmcnt(2)
	ds_write_b128 v44, v[20:23] offset:36864
	s_waitcnt vmcnt(1)
	ds_write_b128 v45, v[24:27]
	s_waitcnt vmcnt(0)
	ds_write_b128 v45, v[28:31] offset:36864
	v_lshl_add_u64 v[0:1], s[58:59], 0, v[42:43]
	v_or_b32_e32 v0, v0, v128
	v_lshl_add_u64 v[164:165], s[52:53], 0, v[0:1]
	v_lshl_add_u64 v[0:1], s[58:59], 0, v[46:47]
	v_or_b32_e32 v0, v0, v128
	v_lshl_add_u64 v[166:167], s[52:53], 0, v[0:1]
	v_or_b32_e32 v42, v42, v128
	v_or_b32_e32 v46, v46, v128
	v_mov_b32_e32 v0, 0
	v_lshl_add_u64 v[172:173], s[54:55], 0, v[42:43]
	v_lshl_add_u64 v[174:175], s[54:55], 0, v[46:47]
	global_load_dwordx4 v[96:99], v[160:161], off
	global_load_dwordx4 v[100:103], v[168:169], off
	global_load_dwordx4 v[104:107], v[162:163], off
	global_load_dwordx4 v[108:111], v[170:171], off
	global_load_dwordx4 v[112:115], v[164:165], off
	global_load_dwordx4 v[116:119], v[172:173], off
	global_load_dwordx4 v[120:123], v[166:167], off
	global_load_dwordx4 v[124:127], v[174:175], off
	s_mov_b64 s[58:59], 0
	v_mov_b32_e32 v1, v0
	v_mov_b32_e32 v2, v0
	v_mov_b32_e32 v3, v0
	v_mov_b32_e32 v4, v0
	v_mov_b32_e32 v5, v0
	v_mov_b32_e32 v6, v0
	v_mov_b32_e32 v7, v0
	v_mov_b32_e32 v8, v0
	v_mov_b32_e32 v9, v0
	v_mov_b32_e32 v10, v0
	v_mov_b32_e32 v11, v0
	v_mov_b32_e32 v12, v0
	v_mov_b32_e32 v13, v0
	v_mov_b32_e32 v14, v0
	v_mov_b32_e32 v15, v0
	v_mov_b32_e32 v16, v0
	v_mov_b32_e32 v17, v0
	v_mov_b32_e32 v18, v0
	v_mov_b32_e32 v19, v0
	v_mov_b32_e32 v20, v0
	v_mov_b32_e32 v21, v0
	v_mov_b32_e32 v22, v0
	v_mov_b32_e32 v23, v0
	v_mov_b32_e32 v24, v0
	v_mov_b32_e32 v25, v0
	v_mov_b32_e32 v26, v0
	v_mov_b32_e32 v27, v0
	v_mov_b32_e32 v28, v0
	v_mov_b32_e32 v29, v0
	v_mov_b32_e32 v30, v0
	v_mov_b32_e32 v31, v0
	v_mov_b32_e32 v32, v0
	v_mov_b32_e32 v33, v0
	v_mov_b32_e32 v34, v0
	v_mov_b32_e32 v35, v0
	v_mov_b32_e32 v36, v0
	v_mov_b32_e32 v37, v0
	v_mov_b32_e32 v38, v0
	v_mov_b32_e32 v39, v0
	v_mov_b32_e32 v40, v0
	v_mov_b32_e32 v41, v0
	v_mov_b32_e32 v42, v0
	v_mov_b32_e32 v43, v0
	v_mov_b32_e32 v44, v0
	v_mov_b32_e32 v45, v0
	v_mov_b32_e32 v46, v0
	v_mov_b32_e32 v47, v0
	v_mov_b32_e32 v48, v0
	v_mov_b32_e32 v49, v0
	v_mov_b32_e32 v50, v0
	v_mov_b32_e32 v51, v0
	v_mov_b32_e32 v52, v0
	v_mov_b32_e32 v53, v0
	v_mov_b32_e32 v54, v0
	v_mov_b32_e32 v55, v0
	v_mov_b32_e32 v56, v0
	v_mov_b32_e32 v57, v0
	v_mov_b32_e32 v58, v0
	v_mov_b32_e32 v59, v0
	v_mov_b32_e32 v60, v0
	v_mov_b32_e32 v61, v0
	v_mov_b32_e32 v62, v0
	v_mov_b32_e32 v63, v0
	s_waitcnt lgkmcnt(0)
	s_barrier
.LBB0_1004:
	s_and_b32 s77, s76, 1
	s_mul_i32 s78, s77, 0x4800
	s_add_u32 s100, s58, 0x80
	s_addc_u32 s101, s59, 0
	v_lshl_add_u64 v[64:65], v[160:161], 0, s[100:101]
	v_lshl_add_u64 v[68:69], v[168:169], 0, s[100:101]
	v_lshl_add_u64 v[72:73], v[162:163], 0, s[100:101]
	v_lshl_add_u64 v[76:77], v[170:171], 0, s[100:101]
	v_lshl_add_u64 v[80:81], v[164:165], 0, s[100:101]
	v_lshl_add_u64 v[84:85], v[172:173], 0, s[100:101]
	v_lshl_add_u64 v[88:89], v[166:167], 0, s[100:101]
	v_lshl_add_u64 v[92:93], v[174:175], 0, s[100:101]
	v_add3_u32 v197, s78, v232, v231
	global_load_dwordx4 v[64:67], v[64:65], off
	s_nop 0
	global_load_dwordx4 v[68:71], v[68:69], off
	s_nop 0
	global_load_dwordx4 v[72:75], v[72:73], off
	s_nop 0
	global_load_dwordx4 v[76:79], v[76:77], off
	s_nop 0
	global_load_dwordx4 v[80:83], v[80:81], off
	s_nop 0
	global_load_dwordx4 v[84:87], v[84:85], off
	s_nop 0
	global_load_dwordx4 v[88:91], v[88:89], off
	s_nop 0
	global_load_dwordx4 v[92:95], v[92:93], off
	v_add3_u32 v198, s78, v234, v231
	ds_read_b128 v[242:245], v198 offset:36864
	ds_read_b128 v[238:241], v197
	ds_read_b128 v[246:249], v197 offset:4608
	ds_read_b128 v[200:203], v197 offset:9216
	ds_read_b128 v[204:207], v197 offset:13824
	s_waitcnt lgkmcnt(3)
	v_mfma_f32_32x32x16_bf16 v[48:63], v[238:241], v[242:245], v[48:63]
	ds_read_b128 v[208:211], v198 offset:36896
	ds_read_b128 v[238:241], v197 offset:32
	s_add_i32 s76, s76, 1
	s_xor_b32 s79, s77, 1
	s_xor_b32 s80, s77, 3
	s_mul_i32 s77, s79, 0x4800
	s_add_u32 s58, s58, 0x80
	s_mul_i32 s78, s80, 0x4800
	s_waitcnt lgkmcnt(4)
	v_mfma_f32_32x32x16_bf16 v[32:47], v[246:249], v[242:245], v[32:47]
	ds_read_b128 v[246:249], v197 offset:4640
	v_or_b32_e32 v250, s77, v128
	s_addc_u32 s59, s59, 0
	v_or_b32_e32 v251, s78, v128
	v_add_u32_e32 v252, v250, v233
	s_cmpk_lg_i32 s58, 0x780
	v_add_u32_e32 v177, v251, v233
	s_waitcnt lgkmcnt(4)
	v_mfma_f32_32x32x16_bf16 v[16:31], v[200:203], v[242:245], v[16:31]
	ds_read_b128 v[200:203], v197 offset:9248
	s_waitcnt lgkmcnt(4)
	v_mfma_f32_32x32x16_bf16 v[0:15], v[204:207], v[242:245], v[0:15]
	ds_read_b128 v[204:207], v197 offset:13856
	s_waitcnt lgkmcnt(3)
	v_mfma_f32_32x32x16_bf16 v[48:63], v[238:241], v[208:211], v[48:63]
	ds_read_b128 v[242:245], v198 offset:36928
	ds_read_b128 v[238:241], v197 offset:64
	s_waitcnt lgkmcnt(4)
	v_mfma_f32_32x32x16_bf16 v[32:47], v[246:249], v[208:211], v[32:47]
	ds_read_b128 v[246:249], v197 offset:4672
	s_waitcnt lgkmcnt(4)
	v_mfma_f32_32x32x16_bf16 v[16:31], v[200:203], v[208:211], v[16:31]
	ds_read_b128 v[200:203], v197 offset:9280
	s_waitcnt lgkmcnt(4)
	v_mfma_f32_32x32x16_bf16 v[0:15], v[204:207], v[208:211], v[0:15]
	ds_read_b128 v[204:207], v197 offset:13888
	s_waitcnt lgkmcnt(3)
	v_mfma_f32_32x32x16_bf16 v[48:63], v[238:241], v[242:245], v[48:63]
	ds_read_b128 v[208:211], v198 offset:36960
	ds_read_b128 v[238:241], v197 offset:96
	s_waitcnt lgkmcnt(4)
	v_mfma_f32_32x32x16_bf16 v[32:47], v[246:249], v[242:245], v[32:47]
	ds_read_b128 v[246:249], v197 offset:4704
	s_waitcnt lgkmcnt(4)
	v_mfma_f32_32x32x16_bf16 v[16:31], v[200:203], v[242:245], v[16:31]
	ds_read_b128 v[200:203], v197 offset:9312
	s_waitcnt lgkmcnt(4)
	v_mfma_f32_32x32x16_bf16 v[0:15], v[204:207], v[242:245], v[0:15]
	ds_read_b128 v[204:207], v197 offset:13920
	s_waitcnt lgkmcnt(3)
	v_mfma_f32_32x32x16_bf16 v[48:63], v[238:241], v[208:211], v[48:63]
	s_waitcnt lgkmcnt(2)
	v_mfma_f32_32x32x16_bf16 v[32:47], v[246:249], v[208:211], v[32:47]
	s_waitcnt lgkmcnt(1)
	v_mfma_f32_32x32x16_bf16 v[16:31], v[200:203], v[208:211], v[16:31]
	v_add_u32_e32 v238, v250, v235
	v_add_u32_e32 v239, v251, v235
	v_add_u32_e32 v240, v250, v236
	v_add_u32_e32 v241, v251, v236
	v_add_u32_e32 v250, v250, v237
	v_add_u32_e32 v251, v251, v237
	s_waitcnt vmcnt(15)
	ds_write_b128 v252, v[96:99]
	s_waitcnt vmcnt(14)
	ds_write_b128 v177, v[100:103]
	s_waitcnt vmcnt(13)
	ds_write_b128 v238, v[104:107]
	s_waitcnt vmcnt(12)
	ds_write_b128 v239, v[108:111]
	s_waitcnt vmcnt(11)
	ds_write_b128 v240, v[112:115]
	s_waitcnt vmcnt(10)
	ds_write_b128 v241, v[116:119]
	s_waitcnt vmcnt(9)
	ds_write_b128 v250, v[120:123]
	s_waitcnt vmcnt(8)
	ds_write_b128 v251, v[124:127]
	s_waitcnt lgkmcnt(8)
	v_mfma_f32_32x32x16_bf16 v[0:15], v[204:207], v[208:211], v[0:15]
	s_waitcnt lgkmcnt(0)
	s_barrier
	s_and_b32 s77, s76, 1
	s_mul_i32 s78, s77, 0x4800
	s_add_u32 s100, s58, 0x80
	s_addc_u32 s101, s59, 0
	v_lshl_add_u64 v[96:97], v[160:161], 0, s[100:101]
	v_lshl_add_u64 v[100:101], v[168:169], 0, s[100:101]
	v_lshl_add_u64 v[104:105], v[162:163], 0, s[100:101]
	v_lshl_add_u64 v[108:109], v[170:171], 0, s[100:101]
	v_lshl_add_u64 v[112:113], v[164:165], 0, s[100:101]
	v_lshl_add_u64 v[116:117], v[172:173], 0, s[100:101]
	v_lshl_add_u64 v[120:121], v[166:167], 0, s[100:101]
	v_lshl_add_u64 v[124:125], v[174:175], 0, s[100:101]
	v_add3_u32 v197, s78, v232, v231
	global_load_dwordx4 v[96:99], v[96:97], off
	s_nop 0
	global_load_dwordx4 v[100:103], v[100:101], off
	s_nop 0
	global_load_dwordx4 v[104:107], v[104:105], off
	s_nop 0
	global_load_dwordx4 v[108:111], v[108:109], off
	s_nop 0
	global_load_dwordx4 v[112:115], v[112:113], off
	s_nop 0
	global_load_dwordx4 v[116:119], v[116:117], off
	s_nop 0
	global_load_dwordx4 v[120:123], v[120:121], off
	s_nop 0
	global_load_dwordx4 v[124:127], v[124:125], off
	v_add3_u32 v198, s78, v234, v231
	ds_read_b128 v[242:245], v198 offset:36864
	ds_read_b128 v[238:241], v197
	ds_read_b128 v[246:249], v197 offset:4608
	ds_read_b128 v[200:203], v197 offset:9216
	ds_read_b128 v[204:207], v197 offset:13824
	s_waitcnt lgkmcnt(3)
	v_mfma_f32_32x32x16_bf16 v[48:63], v[238:241], v[242:245], v[48:63]
	ds_read_b128 v[208:211], v198 offset:36896
	ds_read_b128 v[238:241], v197 offset:32
	s_add_i32 s76, s76, 1
	s_xor_b32 s79, s77, 1
	s_xor_b32 s80, s77, 3
	s_mul_i32 s77, s79, 0x4800
	s_add_u32 s58, s58, 0x80
	s_mul_i32 s78, s80, 0x4800
	s_waitcnt lgkmcnt(4)
	v_mfma_f32_32x32x16_bf16 v[32:47], v[246:249], v[242:245], v[32:47]
	ds_read_b128 v[246:249], v197 offset:4640
	v_or_b32_e32 v250, s77, v128
	s_addc_u32 s59, s59, 0
	v_or_b32_e32 v251, s78, v128
	v_add_u32_e32 v252, v250, v233
	s_cmpk_lg_i32 s58, 0x700
	v_add_u32_e32 v177, v251, v233
	s_waitcnt lgkmcnt(4)
	v_mfma_f32_32x32x16_bf16 v[16:31], v[200:203], v[242:245], v[16:31]
	ds_read_b128 v[200:203], v197 offset:9248
	s_waitcnt lgkmcnt(4)
	v_mfma_f32_32x32x16_bf16 v[0:15], v[204:207], v[242:245], v[0:15]
	ds_read_b128 v[204:207], v197 offset:13856
	s_waitcnt lgkmcnt(3)
	v_mfma_f32_32x32x16_bf16 v[48:63], v[238:241], v[208:211], v[48:63]
	ds_read_b128 v[242:245], v198 offset:36928
	ds_read_b128 v[238:241], v197 offset:64
	s_waitcnt lgkmcnt(4)
	v_mfma_f32_32x32x16_bf16 v[32:47], v[246:249], v[208:211], v[32:47]
	ds_read_b128 v[246:249], v197 offset:4672
	s_waitcnt lgkmcnt(4)
	v_mfma_f32_32x32x16_bf16 v[16:31], v[200:203], v[208:211], v[16:31]
	ds_read_b128 v[200:203], v197 offset:9280
	s_waitcnt lgkmcnt(4)
	v_mfma_f32_32x32x16_bf16 v[0:15], v[204:207], v[208:211], v[0:15]
	ds_read_b128 v[204:207], v197 offset:13888
	s_waitcnt lgkmcnt(3)
	v_mfma_f32_32x32x16_bf16 v[48:63], v[238:241], v[242:245], v[48:63]
	ds_read_b128 v[208:211], v198 offset:36960
	ds_read_b128 v[238:241], v197 offset:96
	s_waitcnt lgkmcnt(4)
	v_mfma_f32_32x32x16_bf16 v[32:47], v[246:249], v[242:245], v[32:47]
	ds_read_b128 v[246:249], v197 offset:4704
	s_waitcnt lgkmcnt(4)
	v_mfma_f32_32x32x16_bf16 v[16:31], v[200:203], v[242:245], v[16:31]
	ds_read_b128 v[200:203], v197 offset:9312
	s_waitcnt lgkmcnt(4)
	v_mfma_f32_32x32x16_bf16 v[0:15], v[204:207], v[242:245], v[0:15]
	ds_read_b128 v[204:207], v197 offset:13920
	s_waitcnt lgkmcnt(3)
	v_mfma_f32_32x32x16_bf16 v[48:63], v[238:241], v[208:211], v[48:63]
	s_waitcnt lgkmcnt(2)
	v_mfma_f32_32x32x16_bf16 v[32:47], v[246:249], v[208:211], v[32:47]
	s_waitcnt lgkmcnt(1)
	v_mfma_f32_32x32x16_bf16 v[16:31], v[200:203], v[208:211], v[16:31]
	v_add_u32_e32 v238, v250, v235
	v_add_u32_e32 v239, v251, v235
	v_add_u32_e32 v240, v250, v236
	v_add_u32_e32 v241, v251, v236
	v_add_u32_e32 v250, v250, v237
	v_add_u32_e32 v251, v251, v237
	s_waitcnt vmcnt(15)
	ds_write_b128 v252, v[64:67]
	s_waitcnt vmcnt(14)
	ds_write_b128 v177, v[68:71]
	s_waitcnt vmcnt(13)
	ds_write_b128 v238, v[72:75]
	s_waitcnt vmcnt(12)
	ds_write_b128 v239, v[76:79]
	s_waitcnt vmcnt(11)
	ds_write_b128 v240, v[80:83]
	s_waitcnt vmcnt(10)
	ds_write_b128 v241, v[84:87]
	s_waitcnt vmcnt(9)
	ds_write_b128 v250, v[88:91]
	s_waitcnt vmcnt(8)
	ds_write_b128 v251, v[92:95]
	s_waitcnt lgkmcnt(8)
	v_mfma_f32_32x32x16_bf16 v[0:15], v[204:207], v[208:211], v[0:15]
	s_waitcnt lgkmcnt(0)
	s_barrier
	s_cbranch_scc1 .LBB0_1004
	s_and_b32 s77, s76, 1
	s_mul_i32 s78, s77, 0x4800
	v_lshl_add_u64 v[250:251], v[130:131], 0, s[98:99]
	v_add3_u32 v197, s78, v232, v231
	v_lshl_add_u64 v[64:65], v[250:251], 0, v[136:137]
	global_load_dwordx4 v[64:67], v[64:65], off
	s_nop 0
	v_lshl_add_u64 v[68:69], v[250:251], 0, v[138:139]
	global_load_dwordx4 v[68:71], v[68:69], off
	s_nop 0
	v_lshl_add_u64 v[72:73], v[250:251], 0, v[140:141]
	global_load_dwordx4 v[72:75], v[72:73], off
	s_nop 0
	v_lshl_add_u64 v[76:77], v[250:251], 0, v[142:143]
	global_load_dwordx4 v[76:79], v[76:77], off
	s_nop 0
	v_lshl_add_u64 v[80:81], v[250:251], 0, v[144:145]
	global_load_dwordx4 v[80:83], v[80:81], off
	s_nop 0
	v_lshl_add_u64 v[84:85], v[250:251], 0, v[146:147]
	global_load_dwordx4 v[84:87], v[84:85], off
	s_nop 0
	v_lshl_add_u64 v[88:89], v[250:251], 0, v[148:149]
	global_load_dwordx4 v[88:91], v[88:89], off
	s_nop 0
	v_lshl_add_u64 v[92:93], v[250:251], 0, v[150:151]
	global_load_dwordx4 v[92:95], v[92:93], off
	v_add3_u32 v198, s78, v234, v231
	ds_read_b128 v[242:245], v198 offset:36864
	ds_read_b128 v[238:241], v197
	ds_read_b128 v[246:249], v197 offset:4608
	ds_read_b128 v[200:203], v197 offset:9216
	ds_read_b128 v[204:207], v197 offset:13824
	s_waitcnt lgkmcnt(3)
	v_mfma_f32_32x32x16_bf16 v[48:63], v[238:241], v[242:245], v[48:63]
	ds_read_b128 v[208:211], v198 offset:36896
	ds_read_b128 v[238:241], v197 offset:32
	s_add_i32 s76, s76, 1
	s_xor_b32 s79, s77, 1
	s_xor_b32 s80, s77, 3
	s_mul_i32 s77, s79, 0x4800
	s_add_u32 s58, s58, 0x80
	s_mul_i32 s78, s80, 0x4800
	s_waitcnt lgkmcnt(4)
	v_mfma_f32_32x32x16_bf16 v[32:47], v[246:249], v[242:245], v[32:47]
	ds_read_b128 v[246:249], v197 offset:4640
	v_or_b32_e32 v250, s77, v128
	s_addc_u32 s59, s59, 0
	v_or_b32_e32 v251, s78, v128
	v_add_u32_e32 v252, v250, v233
	s_cmpk_lg_i32 s58, 0x780
	v_add_u32_e32 v177, v251, v233
	s_waitcnt lgkmcnt(4)
	v_mfma_f32_32x32x16_bf16 v[16:31], v[200:203], v[242:245], v[16:31]
	ds_read_b128 v[200:203], v197 offset:9248
	s_waitcnt lgkmcnt(4)
	v_mfma_f32_32x32x16_bf16 v[0:15], v[204:207], v[242:245], v[0:15]
	ds_read_b128 v[204:207], v197 offset:13856
	s_waitcnt lgkmcnt(3)
	v_mfma_f32_32x32x16_bf16 v[48:63], v[238:241], v[208:211], v[48:63]
	ds_read_b128 v[242:245], v198 offset:36928
	ds_read_b128 v[238:241], v197 offset:64
	s_waitcnt lgkmcnt(4)
	v_mfma_f32_32x32x16_bf16 v[32:47], v[246:249], v[208:211], v[32:47]
	ds_read_b128 v[246:249], v197 offset:4672
	s_waitcnt lgkmcnt(4)
	v_mfma_f32_32x32x16_bf16 v[16:31], v[200:203], v[208:211], v[16:31]
	ds_read_b128 v[200:203], v197 offset:9280
	s_waitcnt lgkmcnt(4)
	v_mfma_f32_32x32x16_bf16 v[0:15], v[204:207], v[208:211], v[0:15]
	ds_read_b128 v[204:207], v197 offset:13888
	s_waitcnt lgkmcnt(3)
	v_mfma_f32_32x32x16_bf16 v[48:63], v[238:241], v[242:245], v[48:63]
	ds_read_b128 v[208:211], v198 offset:36960
	ds_read_b128 v[238:241], v197 offset:96
	s_waitcnt lgkmcnt(4)
	v_mfma_f32_32x32x16_bf16 v[32:47], v[246:249], v[242:245], v[32:47]
	ds_read_b128 v[246:249], v197 offset:4704
	s_waitcnt lgkmcnt(4)
	v_mfma_f32_32x32x16_bf16 v[16:31], v[200:203], v[242:245], v[16:31]
	ds_read_b128 v[200:203], v197 offset:9312
	s_waitcnt lgkmcnt(4)
	v_mfma_f32_32x32x16_bf16 v[0:15], v[204:207], v[242:245], v[0:15]
	ds_read_b128 v[204:207], v197 offset:13920
	s_waitcnt lgkmcnt(3)
	v_mfma_f32_32x32x16_bf16 v[48:63], v[238:241], v[208:211], v[48:63]
	s_waitcnt lgkmcnt(2)
	v_mfma_f32_32x32x16_bf16 v[32:47], v[246:249], v[208:211], v[32:47]
	s_waitcnt lgkmcnt(1)
	v_mfma_f32_32x32x16_bf16 v[16:31], v[200:203], v[208:211], v[16:31]
	v_add_u32_e32 v238, v250, v235
	v_add_u32_e32 v239, v251, v235
	v_add_u32_e32 v240, v250, v236
	v_add_u32_e32 v241, v251, v236
	v_add_u32_e32 v250, v250, v237
	v_add_u32_e32 v251, v251, v237
	s_waitcnt vmcnt(15)
	ds_write_b128 v252, v[96:99]
	s_waitcnt vmcnt(14)
	ds_write_b128 v177, v[100:103]
	s_waitcnt vmcnt(13)
	ds_write_b128 v238, v[104:107]
	s_waitcnt vmcnt(12)
	ds_write_b128 v239, v[108:111]
	s_waitcnt vmcnt(11)
	ds_write_b128 v240, v[112:115]
	s_waitcnt vmcnt(10)
	ds_write_b128 v241, v[116:119]
	s_waitcnt vmcnt(9)
	ds_write_b128 v250, v[120:123]
	s_waitcnt vmcnt(8)
	ds_write_b128 v251, v[124:127]
	s_waitcnt lgkmcnt(8)
	v_mfma_f32_32x32x16_bf16 v[0:15], v[204:207], v[208:211], v[0:15]
	s_waitcnt lgkmcnt(0)
	s_barrier
	v_or_b32_e32 v197, 0x61, v193
	v_or_b32_e32 v198, 0x62, v193
	v_or_b32_e32 v199, 0x63, v193
	v_or_b32_e32 v200, 0x68, v193
	v_or_b32_e32 v201, 0x69, v193
	v_or_b32_e32 v202, 0x6a, v193
	v_or_b32_e32 v203, 0x6b, v193
	v_or_b32_e32 v204, 0x70, v193
	v_or_b32_e32 v205, 0x71, v193
	v_or_b32_e32 v206, 0x72, v193
	v_or_b32_e32 v207, 0x73, v193
	v_or_b32_e32 v208, 0x78, v193
	v_or_b32_e32 v209, 0x79, v193
	v_or_b32_e32 v210, 0x7a, v193
	v_or_b32_e32 v211, 0x7b, v193
	v_add_u32_e32 v108, v232, v231
	ds_read_b128 v[96:99], v108 offset:18432
	v_add_u32_e32 v104, v234, v231
	ds_read_b128 v[100:103], v104 offset:55296
	s_mov_b32 s80, 1
	s_mov_b64 s[58:59], 0
	s_waitcnt lgkmcnt(0)
	v_mfma_f32_32x32x16_bf16 v[48:63], v[96:99], v[100:103], v[48:63]
	ds_read_b128 v[96:99], v108 offset:23040
	s_waitcnt lgkmcnt(0)
	v_mfma_f32_32x32x16_bf16 v[32:47], v[96:99], v[100:103], v[32:47]
	ds_read_b128 v[96:99], v108 offset:27648
	s_waitcnt lgkmcnt(0)
	v_mfma_f32_32x32x16_bf16 v[16:31], v[96:99], v[100:103], v[16:31]
	ds_read_b128 v[96:99], v108 offset:32256
	s_waitcnt lgkmcnt(0)
	v_mfma_f32_32x32x16_bf16 v[0:15], v[96:99], v[100:103], v[0:15]
	ds_read_b128 v[96:99], v108 offset:18464
	ds_read_b128 v[100:103], v104 offset:55328
	s_waitcnt lgkmcnt(0)
	v_mfma_f32_32x32x16_bf16 v[48:63], v[96:99], v[100:103], v[48:63]
	ds_read_b128 v[96:99], v108 offset:23072
	s_waitcnt lgkmcnt(0)
	v_mfma_f32_32x32x16_bf16 v[32:47], v[96:99], v[100:103], v[32:47]
	ds_read_b128 v[96:99], v108 offset:27680
	s_waitcnt lgkmcnt(0)
	v_mfma_f32_32x32x16_bf16 v[16:31], v[96:99], v[100:103], v[16:31]
	ds_read_b128 v[96:99], v108 offset:32288
	s_waitcnt lgkmcnt(0)
	v_mfma_f32_32x32x16_bf16 v[0:15], v[96:99], v[100:103], v[0:15]
	ds_read_b128 v[96:99], v108 offset:18496
	ds_read_b128 v[100:103], v104 offset:55360
	s_waitcnt lgkmcnt(0)
	v_mfma_f32_32x32x16_bf16 v[48:63], v[96:99], v[100:103], v[48:63]
	ds_read_b128 v[96:99], v108 offset:23104
	s_waitcnt lgkmcnt(0)
	v_mfma_f32_32x32x16_bf16 v[32:47], v[96:99], v[100:103], v[32:47]
	ds_read_b128 v[96:99], v108 offset:27712
	s_waitcnt lgkmcnt(0)
	v_mfma_f32_32x32x16_bf16 v[16:31], v[96:99], v[100:103], v[16:31]
	ds_read_b128 v[96:99], v108 offset:32320
	s_waitcnt lgkmcnt(0)
	v_mfma_f32_32x32x16_bf16 v[0:15], v[96:99], v[100:103], v[0:15]
	ds_read_b128 v[96:99], v108 offset:18528
	ds_read_b128 v[100:103], v104 offset:55392
	s_waitcnt lgkmcnt(0)
	v_mfma_f32_32x32x16_bf16 v[48:63], v[96:99], v[100:103], v[48:63]
	ds_read_b128 v[96:99], v108 offset:23136
	ds_read_b128 v[104:107], v108 offset:27744
	ds_read_b128 v[108:111], v108 offset:32352
	s_waitcnt lgkmcnt(0)
	s_barrier
	s_waitcnt vmcnt(0)
	ds_write_b128 v212, v[64:67]
	ds_write_b128 v213, v[68:71]
	ds_write_b128 v214, v[72:75]
	ds_write_b128 v215, v[76:79]
	ds_write_b128 v216, v[80:83]
	ds_write_b128 v217, v[84:87]
	ds_write_b128 v218, v[88:91]
	ds_write_b128 v219, v[92:95]
	s_waitcnt lgkmcnt(0)
	s_barrier
	ds_read2_b64 v[64:67], v196 offset1:2
	v_cvt_pk_bf16_f32 v80, v48, v49
	v_cvt_pk_bf16_f32 v81, v50, v51
	v_cvt_pk_bf16_f32 v82, v52, v53
	v_cvt_pk_bf16_f32 v83, v54, v55
	ds_read2_b64 v[48:51], v196 offset0:4 offset1:6
	v_cvt_pk_bf16_f32 v56, v56, v57
	s_waitcnt lgkmcnt(1)
	v_mfma_f32_32x32x16_bf16 v[64:79], v[64:67], v[80:83], 0
	v_cvt_pk_bf16_f32 v57, v58, v59
	v_cvt_pk_bf16_f32 v58, v60, v61
	v_cvt_pk_bf16_f32 v59, v62, v63
	v_add_u32_e32 v94, 0x4000, v196
	ds_read2_b64 v[90:93], v94 offset0:132 offset1:134
	v_mfma_f32_32x32x16_bf16 v[32:47], v[96:99], v[100:103], v[32:47]
	s_waitcnt lgkmcnt(1)
	v_mfma_f32_32x32x16_bf16 v[64:79], v[48:51], v[56:59], v[64:79]
	ds_read2_b64 v[48:51], v196 offset0:8 offset1:10
	s_nop 8
	v_cvt_pk_bf16_f32 v52, v32, v33
	v_cvt_pk_bf16_f32 v53, v34, v35
	v_cvt_pk_bf16_f32 v54, v36, v37
	v_cvt_pk_bf16_f32 v55, v38, v39
	ds_read2_b64 v[32:35], v196 offset0:12 offset1:14
	s_waitcnt lgkmcnt(1)
	v_mfma_f32_32x32x16_bf16 v[64:79], v[48:51], v[52:55], v[64:79]
	v_cvt_pk_bf16_f32 v48, v40, v41
	v_cvt_pk_bf16_f32 v49, v42, v43
	v_cvt_pk_bf16_f32 v50, v44, v45
	v_cvt_pk_bf16_f32 v51, v46, v47
	v_mfma_f32_32x32x16_bf16 v[16:31], v[104:107], v[100:103], v[16:31]
	s_waitcnt lgkmcnt(0)
	v_mfma_f32_32x32x16_bf16 v[64:79], v[32:35], v[48:51], v[64:79]
	ds_read2_b64 v[32:35], v196 offset0:16 offset1:18
	s_nop 8
	v_cvt_pk_bf16_f32 v44, v16, v17
	v_cvt_pk_bf16_f32 v45, v18, v19
	v_cvt_pk_bf16_f32 v46, v20, v21
	v_cvt_pk_bf16_f32 v47, v22, v23
	ds_read2_b64 v[16:19], v196 offset0:20 offset1:22
	v_cvt_pk_bf16_f32 v40, v24, v25
	s_waitcnt lgkmcnt(1)
	v_mfma_f32_32x32x16_bf16 v[64:79], v[32:35], v[44:47], v[64:79]
	v_cvt_pk_bf16_f32 v41, v26, v27
	v_cvt_pk_bf16_f32 v42, v28, v29
	v_cvt_pk_bf16_f32 v43, v30, v31
	v_add_u32_e32 v24, 0x2000, v196
	v_or_b32_e32 v22, 9, v193
	v_mfma_f32_32x32x16_bf16 v[0:15], v[108:111], v[100:103], v[0:15]
	v_add_u32_e32 v100, 0x6000, v196
	s_waitcnt lgkmcnt(0)
	v_mfma_f32_32x32x16_bf16 v[64:79], v[16:19], v[40:43], v[64:79]
	ds_read2_b64 v[16:19], v196 offset0:24 offset1:26
	s_nop 7
	v_cvt_pk_bf16_f32 v36, v0, v1
	v_cvt_pk_bf16_f32 v37, v2, v3
	v_cvt_pk_bf16_f32 v38, v4, v5
	v_cvt_pk_bf16_f32 v39, v6, v7
	ds_read2_b64 v[0:3], v196 offset0:28 offset1:30
	v_cvt_pk_bf16_f32 v32, v8, v9
	s_waitcnt lgkmcnt(1)
	v_mfma_f32_32x32x16_bf16 v[64:79], v[16:19], v[36:39], v[64:79]
	v_cvt_pk_bf16_f32 v33, v10, v11
	v_cvt_pk_bf16_f32 v34, v12, v13
	v_cvt_pk_bf16_f32 v35, v14, v15
	v_or_b32_e32 v6, 3, v193
	ds_read2_b64 v[16:19], v24 offset0:68 offset1:70
	s_waitcnt lgkmcnt(1)
	v_mfma_f32_32x32x16_bf16 v[64:79], v[0:3], v[32:35], v[64:79]
	v_or_b32_e32 v2, 1, v193
	s_nop 10
	v_ashrrev_i32_e32 v1, 31, v64
	v_and_b32_e32 v0, 0xffffff80, v64
	v_and_b32_e32 v1, 0x7fffffff, v1
	v_bitop3_b32 v60, v0, v1, v193 bitop3:0x36
	v_ashrrev_i32_e32 v1, 31, v65
	v_and_b32_e32 v0, 0xffffff80, v65
	v_and_b32_e32 v1, 0x7fffffff, v1
	v_bitop3_b32 v61, v0, v1, v2 bitop3:0x36
	v_ashrrev_i32_e32 v1, 31, v66
	v_and_b32_e32 v0, 0xffffff80, v66
	v_and_b32_e32 v1, 0x7fffffff, v1
	v_or_b32_e32 v2, 2, v193
	v_bitop3_b32 v62, v0, v1, v2 bitop3:0x36
	ds_read2_b64 v[0:3], v24 offset0:64 offset1:66
	v_ashrrev_i32_e32 v5, 31, v67
	v_and_b32_e32 v4, 0xffffff80, v67
	v_and_b32_e32 v5, 0x7fffffff, v5
	v_bitop3_b32 v63, v4, v5, v6 bitop3:0x36
	v_ashrrev_i32_e32 v5, 31, v68
	v_and_b32_e32 v4, 0xffffff80, v68
	v_and_b32_e32 v5, 0x7fffffff, v5
	v_or_b32_e32 v6, 8, v193
	v_bitop3_b32 v64, v4, v5, v6 bitop3:0x36
	s_waitcnt lgkmcnt(0)
	v_mfma_f32_32x32x16_bf16 v[0:15], v[0:3], v[80:83], 0
	v_ashrrev_i32_e32 v21, 31, v69
	v_and_b32_e32 v20, 0xffffff80, v69
	v_and_b32_e32 v21, 0x7fffffff, v21
	v_bitop3_b32 v68, v20, v21, v22 bitop3:0x36
	v_ashrrev_i32_e32 v20, 31, v70
	v_and_b32_e32 v26, 0x7fffffff, v20
	ds_read2_b64 v[20:23], v24 offset0:72 offset1:74
	v_mfma_f32_32x32x16_bf16 v[0:15], v[16:19], v[56:59], v[0:15]
	v_and_b32_e32 v25, 0xffffff80, v70
	v_or_b32_e32 v16, 10, v193
	v_ashrrev_i32_e32 v17, 31, v71
	v_bitop3_b32 v69, v25, v26, v16 bitop3:0x36
	v_and_b32_e32 v16, 0xffffff80, v71
	v_and_b32_e32 v17, 0x7fffffff, v17
	v_or_b32_e32 v18, 11, v193
	v_bitop3_b32 v70, v16, v17, v18 bitop3:0x36
	ds_read2_b64 v[16:19], v24 offset0:76 offset1:78
	s_waitcnt lgkmcnt(1)
	v_mfma_f32_32x32x16_bf16 v[0:15], v[20:23], v[52:55], v[0:15]
	v_ashrrev_i32_e32 v20, 31, v72
	v_and_b32_e32 v25, 0xffffff80, v72
	v_and_b32_e32 v20, 0x7fffffff, v20
	v_or_b32_e32 v21, 16, v193
	v_bitop3_b32 v71, v25, v20, v21 bitop3:0x36
	v_ashrrev_i32_e32 v20, 31, v73
	v_and_b32_e32 v26, 0x7fffffff, v20
	ds_read2_b64 v[20:23], v24 offset0:80 offset1:82
	s_waitcnt lgkmcnt(1)
	v_mfma_f32_32x32x16_bf16 v[0:15], v[16:19], v[48:51], v[0:15]
	v_and_b32_e32 v25, 0xffffff80, v73
	v_or_b32_e32 v16, 17, v193
	v_ashrrev_i32_e32 v17, 31, v74
	v_bitop3_b32 v72, v25, v26, v16 bitop3:0x36
	v_and_b32_e32 v16, 0xffffff80, v74
	v_and_b32_e32 v17, 0x7fffffff, v17
	v_or_b32_e32 v18, 18, v193
	v_bitop3_b32 v74, v16, v17, v18 bitop3:0x36
	ds_read2_b64 v[16:19], v24 offset0:84 offset1:86
	s_waitcnt lgkmcnt(1)
	v_mfma_f32_32x32x16_bf16 v[0:15], v[20:23], v[44:47], v[0:15]
	v_ashrrev_i32_e32 v20, 31, v75
	v_and_b32_e32 v25, 0xffffff80, v75
	v_and_b32_e32 v20, 0x7fffffff, v20
	v_or_b32_e32 v21, 19, v193
	v_bitop3_b32 v84, v25, v20, v21 bitop3:0x36
	v_ashrrev_i32_e32 v20, 31, v76
	v_and_b32_e32 v26, 0x7fffffff, v20
	ds_read2_b64 v[20:23], v24 offset0:88 offset1:90
	s_waitcnt lgkmcnt(1)
	v_mfma_f32_32x32x16_bf16 v[0:15], v[16:19], v[40:43], v[0:15]
	v_and_b32_e32 v25, 0xffffff80, v76
	v_or_b32_e32 v16, 24, v193
	v_ashrrev_i32_e32 v17, 31, v77
	v_bitop3_b32 v85, v25, v26, v16 bitop3:0x36
	v_and_b32_e32 v16, 0xffffff80, v77
	v_and_b32_e32 v17, 0x7fffffff, v17
	v_or_b32_e32 v18, 25, v193
	v_bitop3_b32 v86, v16, v17, v18 bitop3:0x36
	ds_read2_b64 v[16:19], v24 offset0:92 offset1:94
	s_waitcnt lgkmcnt(1)
	v_mfma_f32_32x32x16_bf16 v[0:15], v[20:23], v[36:39], v[0:15]
	v_ashrrev_i32_e32 v20, 31, v78
	v_and_b32_e32 v25, 0xffffff80, v78
	v_and_b32_e32 v20, 0x7fffffff, v20
	v_or_b32_e32 v21, 26, v193
	v_bitop3_b32 v87, v25, v20, v21 bitop3:0x36
	v_ashrrev_i32_e32 v21, 31, v79
	v_and_b32_e32 v20, 0xffffff80, v79
	s_waitcnt lgkmcnt(0)
	v_mfma_f32_32x32x16_bf16 v[0:15], v[16:19], v[32:35], v[0:15]
	v_or_b32_e32 v17, 32, v193
	v_or_b32_e32 v18, 35, v193
	v_and_b32_e32 v21, 0x7fffffff, v21
	v_or_b32_e32 v22, 27, v193
	v_bitop3_b32 v88, v20, v21, v22 bitop3:0x36
	s_nop 6
	v_and_b32_e32 v16, 0xffffff80, v0
	v_ashrrev_i32_e32 v0, 31, v0
	v_and_b32_e32 v0, 0x7fffffff, v0
	v_bitop3_b32 v65, v16, v0, v17 bitop3:0x36
	v_and_b32_e32 v0, 0xffffff80, v1
	v_ashrrev_i32_e32 v1, 31, v1
	v_and_b32_e32 v1, 0x7fffffff, v1
	v_or_b32_e32 v16, 33, v193
	v_bitop3_b32 v66, v0, v1, v16 bitop3:0x36
	v_ashrrev_i32_e32 v1, 31, v2
	v_and_b32_e32 v0, 0xffffff80, v2
	v_and_b32_e32 v1, 0x7fffffff, v1
	v_or_b32_e32 v2, 34, v193
	v_bitop3_b32 v67, v0, v1, v2 bitop3:0x36
	v_and_b32_e32 v16, 0xffffff80, v3
	v_ashrrev_i32_e32 v17, 31, v3
	ds_read2_b64 v[0:3], v94 offset0:128 offset1:130
	v_and_b32_e32 v17, 0x7fffffff, v17
	v_bitop3_b32 v73, v16, v17, v18 bitop3:0x36
	v_and_b32_e32 v16, 0xffffff80, v4
	v_ashrrev_i32_e32 v4, 31, v4
	v_and_b32_e32 v4, 0x7fffffff, v4
	v_or_b32_e32 v17, 40, v193
	v_bitop3_b32 v75, v16, v4, v17 bitop3:0x36
	s_waitcnt lgkmcnt(0)
	v_mfma_f32_32x32x16_bf16 v[16:31], v[0:3], v[80:83], 0
	v_ashrrev_i32_e32 v0, 31, v5
	v_and_b32_e32 v4, 0xffffff80, v5
	v_and_b32_e32 v0, 0x7fffffff, v0
	v_or_b32_e32 v1, 41, v193
	v_bitop3_b32 v76, v4, v0, v1 bitop3:0x36
	v_ashrrev_i32_e32 v0, 31, v6
	v_and_b32_e32 v5, 0x7fffffff, v0
	ds_read2_b64 v[0:3], v94 offset0:136 offset1:138
	v_mfma_f32_32x32x16_bf16 v[16:31], v[90:93], v[56:59], v[16:31]
	v_and_b32_e32 v4, 0xffffff80, v6
	v_or_b32_e32 v6, 42, v193
	v_bitop3_b32 v77, v4, v5, v6 bitop3:0x36
	v_ashrrev_i32_e32 v5, 31, v7
	v_and_b32_e32 v4, 0xffffff80, v7
	v_and_b32_e32 v5, 0x7fffffff, v5
	v_or_b32_e32 v6, 43, v193
	v_bitop3_b32 v78, v4, v5, v6 bitop3:0x36
	ds_read2_b64 v[4:7], v94 offset0:140 offset1:142
	s_waitcnt lgkmcnt(1)
	v_mfma_f32_32x32x16_bf16 v[16:31], v[0:3], v[52:55], v[16:31]
	v_ashrrev_i32_e32 v0, 31, v8
	v_and_b32_e32 v79, 0xffffff80, v8
	v_and_b32_e32 v0, 0x7fffffff, v0
	v_or_b32_e32 v1, 48, v193
	v_bitop3_b32 v79, v79, v0, v1 bitop3:0x36
	v_ashrrev_i32_e32 v0, 31, v9
	v_and_b32_e32 v8, 0xffffff80, v9
	v_and_b32_e32 v9, 0x7fffffff, v0
	ds_read2_b64 v[0:3], v94 offset0:144 offset1:146
	s_waitcnt lgkmcnt(1)
	v_mfma_f32_32x32x16_bf16 v[16:31], v[4:7], v[48:51], v[16:31]
	v_or_b32_e32 v4, 49, v193
	v_ashrrev_i32_e32 v5, 31, v10
	v_bitop3_b32 v89, v8, v9, v4 bitop3:0x36
	v_and_b32_e32 v4, 0xffffff80, v10
	v_and_b32_e32 v5, 0x7fffffff, v5
	v_or_b32_e32 v6, 50, v193
	v_bitop3_b32 v90, v4, v5, v6 bitop3:0x36
	ds_read2_b64 v[4:7], v94 offset0:148 offset1:150
	s_waitcnt lgkmcnt(1)
	v_mfma_f32_32x32x16_bf16 v[16:31], v[0:3], v[44:47], v[16:31]
	v_ashrrev_i32_e32 v0, 31, v11
	v_and_b32_e32 v8, 0xffffff80, v11
	v_and_b32_e32 v0, 0x7fffffff, v0
	v_or_b32_e32 v1, 51, v193
	v_bitop3_b32 v91, v8, v0, v1 bitop3:0x36
	v_ashrrev_i32_e32 v0, 31, v12
	v_and_b32_e32 v9, 0x7fffffff, v0
	ds_read2_b64 v[0:3], v94 offset0:152 offset1:154
	s_waitcnt lgkmcnt(1)
	v_mfma_f32_32x32x16_bf16 v[16:31], v[4:7], v[40:43], v[16:31]
	v_and_b32_e32 v8, 0xffffff80, v12
	v_or_b32_e32 v4, 56, v193
	v_ashrrev_i32_e32 v5, 31, v13
	v_bitop3_b32 v96, v8, v9, v4 bitop3:0x36
	v_and_b32_e32 v4, 0xffffff80, v13
	v_and_b32_e32 v5, 0x7fffffff, v5
	v_or_b32_e32 v6, 57, v193
	v_bitop3_b32 v97, v4, v5, v6 bitop3:0x36
	ds_read2_b64 v[4:7], v94 offset0:156 offset1:158
	s_waitcnt lgkmcnt(1)
	v_mfma_f32_32x32x16_bf16 v[16:31], v[0:3], v[36:39], v[16:31]
	v_ashrrev_i32_e32 v0, 31, v14
	v_and_b32_e32 v8, 0xffffff80, v14
	v_and_b32_e32 v0, 0x7fffffff, v0
	v_or_b32_e32 v1, 58, v193
	v_bitop3_b32 v98, v8, v0, v1 bitop3:0x36
	v_ashrrev_i32_e32 v1, 31, v15
	v_and_b32_e32 v0, 0xffffff80, v15
	s_waitcnt lgkmcnt(0)
	v_mfma_f32_32x32x16_bf16 v[16:31], v[4:7], v[32:35], v[16:31]
	v_and_b32_e32 v1, 0x7fffffff, v1
	v_or_b32_e32 v2, 59, v193
	v_bitop3_b32 v99, v0, v1, v2 bitop3:0x36
	v_or_b32_e32 v2, 64, v193
	v_or_b32_e32 v6, 0x43, v193
	ds_read2_b64 v[92:95], v100 offset0:196 offset1:198
	s_nop 5
	v_ashrrev_i32_e32 v1, 31, v16
	v_and_b32_e32 v0, 0xffffff80, v16
	v_and_b32_e32 v1, 0x7fffffff, v1
	v_bitop3_b32 v16, v0, v1, v2 bitop3:0x36
	v_ashrrev_i32_e32 v1, 31, v17
	v_and_b32_e32 v0, 0xffffff80, v17
	v_and_b32_e32 v1, 0x7fffffff, v1
	v_or_b32_e32 v2, 0x41, v193
	v_bitop3_b32 v17, v0, v1, v2 bitop3:0x36
	v_ashrrev_i32_e32 v1, 31, v18
	v_and_b32_e32 v0, 0xffffff80, v18
	v_and_b32_e32 v1, 0x7fffffff, v1
	v_or_b32_e32 v2, 0x42, v193
	v_bitop3_b32 v18, v0, v1, v2 bitop3:0x36
	ds_read2_b64 v[0:3], v100 offset0:192 offset1:194
	v_ashrrev_i32_e32 v5, 31, v19
	v_and_b32_e32 v4, 0xffffff80, v19
	v_and_b32_e32 v5, 0x7fffffff, v5
	v_bitop3_b32 v19, v4, v5, v6 bitop3:0x36
	v_ashrrev_i32_e32 v5, 31, v20
	v_and_b32_e32 v4, 0xffffff80, v20
	v_and_b32_e32 v5, 0x7fffffff, v5
	v_or_b32_e32 v6, 0x48, v193
	v_bitop3_b32 v20, v4, v5, v6 bitop3:0x36
	s_waitcnt lgkmcnt(0)
	v_mfma_f32_32x32x16_bf16 v[0:15], v[0:3], v[80:83], 0
	v_and_b32_e32 v101, 0xffffff80, v21
	v_ashrrev_i32_e32 v21, 31, v21
	v_and_b32_e32 v21, 0x7fffffff, v21
	v_or_b32_e32 v80, 0x49, v193
	v_bitop3_b32 v21, v101, v21, v80 bitop3:0x36
	ds_read2_b64 v[80:83], v100 offset0:200 offset1:202
	v_and_b32_e32 v101, 0xffffff80, v22
	v_mfma_f32_32x32x16_bf16 v[0:15], v[92:95], v[56:59], v[0:15]
	v_ashrrev_i32_e32 v22, 31, v22
	v_and_b32_e32 v22, 0x7fffffff, v22
	v_or_b32_e32 v56, 0x4a, v193
	v_bitop3_b32 v92, v101, v22, v56 bitop3:0x36
	v_and_b32_e32 v22, 0xffffff80, v23
	v_ashrrev_i32_e32 v23, 31, v23
	v_and_b32_e32 v23, 0x7fffffff, v23
	v_or_b32_e32 v56, 0x4b, v193
	v_bitop3_b32 v93, v22, v23, v56 bitop3:0x36
	ds_read2_b64 v[56:59], v100 offset0:204 offset1:206
	s_waitcnt lgkmcnt(1)
	v_mfma_f32_32x32x16_bf16 v[0:15], v[80:83], v[52:55], v[0:15]
	v_ashrrev_i32_e32 v23, 31, v24
	v_and_b32_e32 v22, 0xffffff80, v24
	v_and_b32_e32 v23, 0x7fffffff, v23
	v_or_b32_e32 v24, 0x50, v193
	v_bitop3_b32 v52, v22, v23, v24 bitop3:0x36
	v_ashrrev_i32_e32 v22, 31, v25
	v_and_b32_e32 v53, 0xffffff80, v25
	v_and_b32_e32 v54, 0x7fffffff, v22
	ds_read2_b64 v[22:25], v100 offset0:208 offset1:210
	s_waitcnt lgkmcnt(1)
	v_mfma_f32_32x32x16_bf16 v[0:15], v[56:59], v[48:51], v[0:15]
	v_or_b32_e32 v48, 0x51, v193
	v_bitop3_b32 v53, v53, v54, v48 bitop3:0x36
	v_and_b32_e32 v48, 0xffffff80, v26
	v_ashrrev_i32_e32 v26, 31, v26
	v_and_b32_e32 v26, 0x7fffffff, v26
	v_or_b32_e32 v49, 0x52, v193
	v_bitop3_b32 v54, v48, v26, v49 bitop3:0x36
	ds_read2_b64 v[48:51], v100 offset0:212 offset1:214
	s_waitcnt lgkmcnt(1)
	v_mfma_f32_32x32x16_bf16 v[0:15], v[22:25], v[44:47], v[0:15]
	v_ashrrev_i32_e32 v22, 31, v27
	v_and_b32_e32 v26, 0xffffff80, v27
	v_and_b32_e32 v22, 0x7fffffff, v22
	v_or_b32_e32 v23, 0x53, v193
	v_bitop3_b32 v44, v26, v22, v23 bitop3:0x36
	v_ashrrev_i32_e32 v22, 31, v28
	v_and_b32_e32 v27, 0x7fffffff, v22
	ds_read2_b64 v[22:25], v100 offset0:216 offset1:218
	s_waitcnt lgkmcnt(1)
	v_mfma_f32_32x32x16_bf16 v[0:15], v[48:51], v[40:43], v[0:15]
	v_and_b32_e32 v26, 0xffffff80, v28
	v_or_b32_e32 v28, 0x58, v193
	v_bitop3_b32 v40, v26, v27, v28 bitop3:0x36
	v_ashrrev_i32_e32 v27, 31, v29
	v_and_b32_e32 v26, 0xffffff80, v29
	v_and_b32_e32 v27, 0x7fffffff, v27
	v_or_b32_e32 v28, 0x59, v193
	v_bitop3_b32 v41, v26, v27, v28 bitop3:0x36
	ds_read2_b64 v[26:29], v100 offset0:220 offset1:222
	s_waitcnt lgkmcnt(1)
	v_mfma_f32_32x32x16_bf16 v[0:15], v[22:25], v[36:39], v[0:15]
	v_ashrrev_i32_e32 v22, 31, v30
	v_and_b32_e32 v42, 0xffffff80, v30
	v_and_b32_e32 v22, 0x7fffffff, v22
	v_or_b32_e32 v23, 0x5a, v193
	v_ashrrev_i32_e32 v24, 31, v31
	v_bitop3_b32 v22, v42, v22, v23 bitop3:0x36
	v_and_b32_e32 v23, 0xffffff80, v31
	s_waitcnt lgkmcnt(0)
	v_mfma_f32_32x32x16_bf16 v[0:15], v[26:29], v[32:35], v[0:15]
	v_and_b32_e32 v24, 0x7fffffff, v24
	v_or_b32_e32 v25, 0x5b, v193
	v_bitop3_b32 v23, v23, v24, v25 bitop3:0x36
	v_or_b32_e32 v25, 0x60, v193
	v_max_i32_e32 v26, v63, v62
	v_min_i32_e32 v27, v63, v62
	v_max_i32_e32 v28, v64, v68
	s_nop 4
	v_and_b32_e32 v24, 0xffffff80, v0
	v_ashrrev_i32_e32 v0, 31, v0
	v_and_b32_e32 v0, 0x7fffffff, v0
	v_bitop3_b32 v0, v24, v0, v25 bitop3:0x36
	v_and_b32_e32 v24, 0xffffff80, v1
	v_ashrrev_i32_e32 v1, 31, v1
	v_and_b32_e32 v1, 0x7fffffff, v1
	v_bitop3_b32 v1, v24, v1, v197 bitop3:0x36
	v_and_b32_e32 v24, 0xffffff80, v2
	v_ashrrev_i32_e32 v2, 31, v2
	v_and_b32_e32 v2, 0x7fffffff, v2
	v_bitop3_b32 v2, v24, v2, v198 bitop3:0x36
	v_and_b32_e32 v24, 0xffffff80, v3
	v_ashrrev_i32_e32 v3, 31, v3
	v_and_b32_e32 v3, 0x7fffffff, v3
	v_bitop3_b32 v3, v24, v3, v199 bitop3:0x36
	v_and_b32_e32 v24, 0xffffff80, v4
	v_ashrrev_i32_e32 v4, 31, v4
	v_and_b32_e32 v4, 0x7fffffff, v4
	v_bitop3_b32 v4, v24, v4, v200 bitop3:0x36
	v_and_b32_e32 v24, 0xffffff80, v5
	v_ashrrev_i32_e32 v5, 31, v5
	v_and_b32_e32 v5, 0x7fffffff, v5
	v_bitop3_b32 v5, v24, v5, v201 bitop3:0x36
	v_and_b32_e32 v24, 0xffffff80, v6
	v_ashrrev_i32_e32 v6, 31, v6
	v_and_b32_e32 v6, 0x7fffffff, v6
	v_bitop3_b32 v6, v24, v6, v202 bitop3:0x36
	v_and_b32_e32 v24, 0xffffff80, v7
	v_ashrrev_i32_e32 v7, 31, v7
	v_and_b32_e32 v7, 0x7fffffff, v7
	v_bitop3_b32 v7, v24, v7, v203 bitop3:0x36
	v_and_b32_e32 v24, 0xffffff80, v8
	v_ashrrev_i32_e32 v8, 31, v8
	v_and_b32_e32 v8, 0x7fffffff, v8
	v_bitop3_b32 v8, v24, v8, v204 bitop3:0x36
	v_and_b32_e32 v24, 0xffffff80, v9
	v_ashrrev_i32_e32 v9, 31, v9
	v_and_b32_e32 v9, 0x7fffffff, v9
	v_bitop3_b32 v9, v24, v9, v205 bitop3:0x36
	v_and_b32_e32 v24, 0xffffff80, v10
	v_ashrrev_i32_e32 v10, 31, v10
	v_and_b32_e32 v10, 0x7fffffff, v10
	v_bitop3_b32 v10, v24, v10, v206 bitop3:0x36
	v_and_b32_e32 v24, 0xffffff80, v11
	v_ashrrev_i32_e32 v11, 31, v11
	v_and_b32_e32 v11, 0x7fffffff, v11
	v_bitop3_b32 v11, v24, v11, v207 bitop3:0x36
	v_and_b32_e32 v24, 0xffffff80, v12
	v_ashrrev_i32_e32 v12, 31, v12
	v_and_b32_e32 v12, 0x7fffffff, v12
	v_bitop3_b32 v12, v24, v12, v208 bitop3:0x36
	v_and_b32_e32 v24, 0xffffff80, v13
	v_ashrrev_i32_e32 v13, 31, v13
	v_and_b32_e32 v13, 0x7fffffff, v13
	v_bitop3_b32 v13, v24, v13, v209 bitop3:0x36
	v_and_b32_e32 v24, 0xffffff80, v14
	v_ashrrev_i32_e32 v14, 31, v14
	v_and_b32_e32 v14, 0x7fffffff, v14
	v_bitop3_b32 v14, v24, v14, v210 bitop3:0x36
	v_and_b32_e32 v24, 0xffffff80, v15
	v_ashrrev_i32_e32 v15, 31, v15
	v_and_b32_e32 v15, 0x7fffffff, v15
	v_bitop3_b32 v15, v24, v15, v211 bitop3:0x36
	v_max_i32_e32 v24, v60, v61
	v_min_i32_e32 v25, v60, v61
	v_min_i32_e32 v29, v64, v68
	v_max_i32_e32 v30, v70, v69
	v_min_i32_e32 v31, v70, v69
	v_max_i32_e32 v32, v71, v72
	v_min_i32_e32 v33, v71, v72
	v_max_i32_e32 v34, v84, v74
	v_min_i32_e32 v35, v84, v74
	v_max_i32_e32 v36, v85, v86
	v_min_i32_e32 v37, v85, v86
	v_max_i32_e32 v38, v88, v87
	v_min_i32_e32 v39, v88, v87
	v_max_i32_e32 v51, v65, v66
	v_min_i32_e32 v55, v65, v66
	v_max_i32_e32 v56, v73, v67
	v_min_i32_e32 v57, v73, v67
	v_max_i32_e32 v58, v75, v76
	v_min_i32_e32 v59, v75, v76
	v_max_i32_e32 v60, v78, v77
	v_min_i32_e32 v61, v78, v77
	v_max_i32_e32 v62, v79, v89
	v_min_i32_e32 v63, v79, v89
	v_max_i32_e32 v64, v91, v90
	v_min_i32_e32 v65, v91, v90
	v_max_i32_e32 v66, v96, v97
	v_min_i32_e32 v67, v96, v97
	v_max_i32_e32 v68, v99, v98
	v_min_i32_e32 v69, v99, v98
	v_max_i32_e32 v78, v16, v17
	v_min_i32_e32 v16, v16, v17
	v_max_i32_e32 v17, v19, v18
	v_min_i32_e32 v18, v19, v18
	v_max_i32_e32 v19, v20, v21
	v_min_i32_e32 v20, v20, v21
	v_max_i32_e32 v21, v93, v92
	v_min_i32_e32 v79, v93, v92
	v_max_i32_e32 v80, v52, v53
	v_min_i32_e32 v52, v52, v53
	v_max_i32_e32 v53, v44, v54
	v_min_i32_e32 v44, v44, v54
	v_max_i32_e32 v54, v40, v41
	v_min_i32_e32 v40, v40, v41
	v_max_i32_e32 v41, v23, v22
	v_min_i32_e32 v22, v23, v22
	v_max_i32_e32 v88, v0, v1
	v_min_i32_e32 v0, v0, v1
	v_max_i32_e32 v1, v3, v2
	v_min_i32_e32 v2, v3, v2
	v_max_i32_e32 v3, v4, v5
	v_min_i32_e32 v4, v4, v5
	v_max_i32_e32 v5, v7, v6
	v_min_i32_e32 v6, v7, v6
	v_max_i32_e32 v7, v8, v9
	v_min_i32_e32 v8, v8, v9
	v_max_i32_e32 v9, v11, v10
	v_min_i32_e32 v10, v11, v10
	v_max_i32_e32 v11, v12, v13
	v_min_i32_e32 v12, v12, v13
	v_max_i32_e32 v13, v15, v14
	v_min_i32_e32 v14, v15, v14
	v_max_i32_e32 v42, v24, v27
	v_min_i32_e32 v24, v24, v27
	v_max_i32_e32 v27, v25, v26
	v_min_i32_e32 v25, v25, v26
	v_max_i32_e32 v26, v31, v28
	v_min_i32_e32 v28, v31, v28
	v_max_i32_e32 v31, v30, v29
	v_min_i32_e32 v29, v30, v29
	v_max_i32_e32 v30, v32, v35
	v_min_i32_e32 v32, v32, v35
	v_max_i32_e32 v35, v33, v34
	v_min_i32_e32 v33, v33, v34
	v_max_i32_e32 v34, v39, v36
	v_min_i32_e32 v36, v39, v36
	v_max_i32_e32 v39, v38, v37
	v_min_i32_e32 v37, v38, v37
	v_max_i32_e32 v70, v51, v57
	v_min_i32_e32 v51, v51, v57
	v_max_i32_e32 v57, v55, v56
	v_min_i32_e32 v55, v55, v56
	v_max_i32_e32 v56, v61, v58
	v_min_i32_e32 v58, v61, v58
	v_max_i32_e32 v61, v60, v59
	v_min_i32_e32 v59, v60, v59
	v_max_i32_e32 v60, v62, v65
	v_min_i32_e32 v62, v62, v65
	v_max_i32_e32 v65, v63, v64
	v_min_i32_e32 v63, v63, v64
	v_max_i32_e32 v64, v69, v66
	v_min_i32_e32 v66, v69, v66
	v_max_i32_e32 v69, v68, v67
	v_min_i32_e32 v67, v68, v67
	v_max_i32_e32 v23, v78, v18
	v_min_i32_e32 v18, v78, v18
	v_max_i32_e32 v78, v16, v17
	v_min_i32_e32 v16, v16, v17
	v_max_i32_e32 v17, v79, v19
	v_min_i32_e32 v19, v79, v19
	v_max_i32_e32 v79, v21, v20
	v_min_i32_e32 v20, v21, v20
	v_max_i32_e32 v21, v80, v44
	v_min_i32_e32 v44, v80, v44
	v_max_i32_e32 v80, v52, v53
	v_min_i32_e32 v52, v52, v53
	v_max_i32_e32 v53, v22, v54
	v_min_i32_e32 v22, v22, v54
	v_max_i32_e32 v54, v41, v40
	v_min_i32_e32 v40, v41, v40
	v_max_i32_e32 v15, v88, v2
	v_min_i32_e32 v2, v88, v2
	v_max_i32_e32 v88, v0, v1
	v_min_i32_e32 v0, v0, v1
	v_max_i32_e32 v1, v6, v3
	v_min_i32_e32 v3, v6, v3
	v_max_i32_e32 v6, v5, v4
	v_min_i32_e32 v4, v5, v4
	v_max_i32_e32 v5, v7, v10
	v_min_i32_e32 v7, v7, v10
	v_max_i32_e32 v10, v8, v9
	v_min_i32_e32 v8, v8, v9
	v_max_i32_e32 v9, v14, v11
	v_min_i32_e32 v11, v14, v11
	v_max_i32_e32 v14, v13, v12
	v_min_i32_e32 v12, v13, v12
	v_max_i32_e32 v38, v42, v27
	v_min_i32_e32 v27, v42, v27
	v_max_i32_e32 v42, v24, v25
	v_min_i32_e32 v24, v24, v25
	v_max_i32_e32 v25, v29, v28
	v_min_i32_e32 v28, v29, v28
	v_max_i32_e32 v29, v31, v26
	v_min_i32_e32 v26, v31, v26
	v_max_i32_e32 v31, v30, v35
	v_min_i32_e32 v30, v30, v35
	v_max_i32_e32 v35, v32, v33
	v_min_i32_e32 v32, v32, v33
	v_max_i32_e32 v33, v37, v36
	v_min_i32_e32 v36, v37, v36
	v_max_i32_e32 v37, v39, v34
	v_min_i32_e32 v34, v39, v34
	v_max_i32_e32 v68, v70, v57
	v_min_i32_e32 v57, v70, v57
	v_max_i32_e32 v70, v51, v55
	v_min_i32_e32 v51, v51, v55
	v_max_i32_e32 v55, v59, v58
	v_min_i32_e32 v58, v59, v58
	v_max_i32_e32 v59, v61, v56
	v_min_i32_e32 v56, v61, v56
	v_max_i32_e32 v61, v60, v65
	v_min_i32_e32 v60, v60, v65
	v_max_i32_e32 v65, v62, v63
	v_min_i32_e32 v62, v62, v63
	v_max_i32_e32 v63, v67, v66
	v_min_i32_e32 v66, v67, v66
	v_max_i32_e32 v67, v69, v64
	v_min_i32_e32 v64, v69, v64
	v_max_i32_e32 v41, v23, v78
	v_min_i32_e32 v23, v23, v78
	v_max_i32_e32 v78, v18, v16
	v_min_i32_e32 v16, v18, v16
	v_max_i32_e32 v18, v20, v19
	v_min_i32_e32 v19, v20, v19
	v_max_i32_e32 v20, v79, v17
	v_min_i32_e32 v17, v79, v17
	v_max_i32_e32 v79, v21, v80
	v_min_i32_e32 v21, v21, v80
	v_max_i32_e32 v80, v44, v52
	v_min_i32_e32 v44, v44, v52
	v_max_i32_e32 v52, v40, v22
	v_min_i32_e32 v22, v40, v22
	v_max_i32_e32 v40, v54, v53
	v_min_i32_e32 v53, v54, v53
	v_max_i32_e32 v13, v15, v88
	v_min_i32_e32 v15, v15, v88
	v_max_i32_e32 v88, v2, v0
	v_min_i32_e32 v0, v2, v0
	v_max_i32_e32 v2, v4, v3
	v_min_i32_e32 v3, v4, v3
	v_max_i32_e32 v4, v6, v1
	v_min_i32_e32 v1, v6, v1
	v_max_i32_e32 v6, v5, v10
	v_min_i32_e32 v5, v5, v10
	v_max_i32_e32 v10, v7, v8
	v_min_i32_e32 v7, v7, v8
	v_max_i32_e32 v8, v12, v11
	v_min_i32_e32 v11, v12, v11
	v_max_i32_e32 v12, v14, v9
	v_min_i32_e32 v9, v14, v9
	v_max_i32_e32 v39, v38, v28
	v_min_i32_e32 v28, v38, v28
	v_max_i32_e32 v38, v27, v25
	v_min_i32_e32 v25, v27, v25
	v_max_i32_e32 v27, v42, v26
	v_min_i32_e32 v26, v42, v26
	v_max_i32_e32 v42, v24, v29
	v_min_i32_e32 v24, v24, v29
	v_max_i32_e32 v29, v36, v31
	v_min_i32_e32 v31, v36, v31
	v_max_i32_e32 v36, v33, v30
	v_min_i32_e32 v30, v33, v30
	v_max_i32_e32 v33, v34, v35
	v_min_i32_e32 v34, v34, v35
	v_max_i32_e32 v35, v37, v32
	v_min_i32_e32 v32, v37, v32
	v_max_i32_e32 v69, v68, v58
	v_min_i32_e32 v58, v68, v58
	v_max_i32_e32 v68, v57, v55
	v_min_i32_e32 v55, v57, v55
	v_max_i32_e32 v57, v70, v56
	v_min_i32_e32 v56, v70, v56
	v_max_i32_e32 v70, v51, v59
	v_min_i32_e32 v51, v51, v59
	v_max_i32_e32 v59, v66, v61
	v_min_i32_e32 v61, v66, v61
	v_max_i32_e32 v66, v63, v60
	v_min_i32_e32 v60, v63, v60
	v_max_i32_e32 v63, v64, v65
	v_min_i32_e32 v64, v64, v65
	v_max_i32_e32 v65, v67, v62
	v_min_i32_e32 v62, v67, v62
	v_max_i32_e32 v54, v41, v19
	v_min_i32_e32 v19, v41, v19
	v_max_i32_e32 v41, v23, v18
	v_min_i32_e32 v18, v23, v18
	v_max_i32_e32 v23, v78, v17
	v_min_i32_e32 v17, v78, v17
	v_max_i32_e32 v78, v16, v20
	v_min_i32_e32 v16, v16, v20
	v_max_i32_e32 v20, v22, v79
	v_min_i32_e32 v22, v22, v79
	v_max_i32_e32 v79, v52, v21
	v_min_i32_e32 v21, v52, v21
	v_max_i32_e32 v52, v53, v80
	v_min_i32_e32 v53, v53, v80
	v_max_i32_e32 v80, v40, v44
	v_min_i32_e32 v40, v40, v44
	v_max_i32_e32 v14, v13, v3
	v_min_i32_e32 v3, v13, v3
	v_max_i32_e32 v13, v15, v2
	v_min_i32_e32 v2, v15, v2
	v_max_i32_e32 v15, v88, v1
	v_min_i32_e32 v1, v88, v1
	v_max_i32_e32 v88, v0, v4
	v_min_i32_e32 v0, v0, v4
	v_max_i32_e32 v4, v11, v6
	v_min_i32_e32 v6, v11, v6
	v_max_i32_e32 v11, v8, v5
	v_min_i32_e32 v5, v8, v5
	v_max_i32_e32 v8, v9, v10
	v_min_i32_e32 v9, v9, v10
	v_max_i32_e32 v10, v12, v7
	v_min_i32_e32 v7, v12, v7
	v_max_i32_e32 v37, v39, v27
	v_min_i32_e32 v27, v39, v27
	v_max_i32_e32 v39, v38, v42
	v_min_i32_e32 v38, v38, v42
	v_max_i32_e32 v42, v28, v26
	v_min_i32_e32 v26, v28, v26
	v_max_i32_e32 v28, v25, v24
	v_min_i32_e32 v24, v25, v24
	v_max_i32_e32 v25, v34, v31
	v_min_i32_e32 v31, v34, v31
	v_max_i32_e32 v34, v32, v30
	v_min_i32_e32 v30, v32, v30
	v_max_i32_e32 v32, v33, v29
	v_min_i32_e32 v29, v33, v29
	v_max_i32_e32 v33, v35, v36
	v_min_i32_e32 v35, v35, v36
	v_max_i32_e32 v67, v69, v57
	v_min_i32_e32 v57, v69, v57
	v_max_i32_e32 v69, v68, v70
	v_min_i32_e32 v68, v68, v70
	v_max_i32_e32 v70, v58, v56
	v_min_i32_e32 v56, v58, v56
	v_max_i32_e32 v58, v55, v51
	v_min_i32_e32 v51, v55, v51
	v_max_i32_e32 v55, v64, v61
	v_min_i32_e32 v61, v64, v61
	v_max_i32_e32 v64, v62, v60
	v_min_i32_e32 v60, v62, v60
	v_max_i32_e32 v62, v63, v59
	v_min_i32_e32 v59, v63, v59
	v_max_i32_e32 v63, v65, v66
	v_min_i32_e32 v65, v65, v66
	v_max_i32_e32 v44, v54, v23
	v_min_i32_e32 v23, v54, v23
	v_max_i32_e32 v54, v41, v78
	v_min_i32_e32 v41, v41, v78
	v_max_i32_e32 v78, v19, v17
	v_min_i32_e32 v17, v19, v17
	v_max_i32_e32 v19, v18, v16
	v_min_i32_e32 v16, v18, v16
	v_max_i32_e32 v18, v53, v22
	v_min_i32_e32 v22, v53, v22
	v_max_i32_e32 v53, v40, v21
	v_min_i32_e32 v21, v40, v21
	v_max_i32_e32 v40, v52, v20
	v_min_i32_e32 v20, v52, v20
	v_max_i32_e32 v52, v80, v79
	v_min_i32_e32 v79, v80, v79
	v_max_i32_e32 v12, v14, v15
	v_min_i32_e32 v14, v14, v15
	v_max_i32_e32 v15, v13, v88
	v_min_i32_e32 v13, v13, v88
	v_max_i32_e32 v88, v3, v1
	v_min_i32_e32 v1, v3, v1
	v_max_i32_e32 v3, v2, v0
	v_min_i32_e32 v0, v2, v0
	v_max_i32_e32 v2, v9, v6
	v_min_i32_e32 v6, v9, v6
	v_max_i32_e32 v9, v7, v5
	v_min_i32_e32 v5, v7, v5
	v_max_i32_e32 v7, v8, v4
	v_min_i32_e32 v4, v8, v4
	v_max_i32_e32 v8, v10, v11
	v_min_i32_e32 v10, v10, v11
	v_max_i32_e32 v36, v37, v39
	v_min_i32_e32 v37, v37, v39
	v_max_i32_e32 v39, v27, v38
	v_min_i32_e32 v27, v27, v38
	v_max_i32_e32 v38, v42, v28
	v_min_i32_e32 v28, v42, v28
	v_max_i32_e32 v42, v26, v24
	v_min_i32_e32 v24, v26, v24
	v_max_i32_e32 v26, v30, v31
	v_min_i32_e32 v30, v30, v31
	v_max_i32_e32 v31, v34, v25
	v_min_i32_e32 v25, v34, v25
	v_max_i32_e32 v34, v35, v29
	v_min_i32_e32 v29, v35, v29
	v_max_i32_e32 v35, v33, v32
	v_min_i32_e32 v32, v33, v32
	v_max_i32_e32 v66, v67, v69
	v_min_i32_e32 v67, v67, v69
	v_max_i32_e32 v69, v57, v68
	v_min_i32_e32 v57, v57, v68
	v_max_i32_e32 v68, v70, v58
	v_min_i32_e32 v58, v70, v58
	v_max_i32_e32 v70, v56, v51
	v_min_i32_e32 v51, v56, v51
	v_max_i32_e32 v56, v60, v61
	v_min_i32_e32 v60, v60, v61
	v_max_i32_e32 v61, v64, v55
	v_min_i32_e32 v55, v64, v55
	v_max_i32_e32 v64, v65, v59
	v_min_i32_e32 v59, v65, v59
	v_max_i32_e32 v65, v63, v62
	v_min_i32_e32 v62, v63, v62
	v_max_i32_e32 v80, v44, v54
	v_min_i32_e32 v44, v44, v54
	v_max_i32_e32 v54, v23, v41
	v_min_i32_e32 v23, v23, v41
	v_max_i32_e32 v41, v78, v19
	v_min_i32_e32 v19, v78, v19
	v_max_i32_e32 v78, v17, v16
	v_min_i32_e32 v16, v17, v16
	v_max_i32_e32 v17, v21, v22
	v_min_i32_e32 v21, v21, v22
	v_max_i32_e32 v22, v53, v18
	v_min_i32_e32 v18, v53, v18
	v_max_i32_e32 v53, v79, v20
	v_min_i32_e32 v20, v79, v20
	v_max_i32_e32 v79, v52, v40
	v_min_i32_e32 v40, v52, v40
	v_max_i32_e32 v11, v12, v15
	v_min_i32_e32 v12, v12, v15
	v_max_i32_e32 v15, v14, v13
	v_min_i32_e32 v13, v14, v13
	v_max_i32_e32 v14, v88, v3
	v_min_i32_e32 v3, v88, v3
	v_max_i32_e32 v88, v1, v0
	v_min_i32_e32 v0, v1, v0
	v_max_i32_e32 v1, v5, v6
	v_min_i32_e32 v5, v5, v6
	v_max_i32_e32 v6, v9, v2
	v_min_i32_e32 v2, v9, v2
	v_max_i32_e32 v9, v10, v4
	v_min_i32_e32 v4, v10, v4
	v_max_i32_e32 v10, v8, v7
	v_min_i32_e32 v7, v8, v7
	v_max_i32_e32 v33, v36, v30
	v_min_i32_e32 v30, v36, v30
	v_max_i32_e32 v36, v37, v26
	v_min_i32_e32 v26, v37, v26
	v_max_i32_e32 v37, v39, v25
	v_min_i32_e32 v25, v39, v25
	v_max_i32_e32 v39, v27, v31
	v_min_i32_e32 v27, v27, v31
	v_max_i32_e32 v31, v38, v29
	v_min_i32_e32 v29, v38, v29
	v_max_i32_e32 v38, v28, v34
	v_min_i32_e32 v28, v28, v34
	v_max_i32_e32 v34, v42, v32
	v_min_i32_e32 v32, v42, v32
	v_max_i32_e32 v42, v24, v35
	v_min_i32_e32 v24, v24, v35
	v_max_i32_e32 v63, v66, v60
	v_min_i32_e32 v60, v66, v60
	v_max_i32_e32 v66, v67, v56
	v_min_i32_e32 v56, v67, v56
	v_max_i32_e32 v67, v69, v55
	v_min_i32_e32 v55, v69, v55
	v_max_i32_e32 v69, v57, v61
	v_min_i32_e32 v57, v57, v61
	v_max_i32_e32 v61, v68, v59
	v_min_i32_e32 v59, v68, v59
	v_max_i32_e32 v68, v58, v64
	v_min_i32_e32 v58, v58, v64
	v_max_i32_e32 v64, v70, v62
	v_min_i32_e32 v62, v70, v62
	v_max_i32_e32 v70, v51, v65
	v_min_i32_e32 v51, v51, v65
	v_max_i32_e32 v52, v80, v21
	v_min_i32_e32 v21, v80, v21
	v_max_i32_e32 v80, v44, v17
	v_min_i32_e32 v17, v44, v17
	v_max_i32_e32 v44, v54, v18
	v_min_i32_e32 v18, v54, v18
	v_max_i32_e32 v54, v23, v22
	v_min_i32_e32 v22, v23, v22
	v_max_i32_e32 v23, v41, v20
	v_min_i32_e32 v20, v41, v20
	v_max_i32_e32 v41, v19, v53
	v_min_i32_e32 v19, v19, v53
	v_max_i32_e32 v53, v78, v40
	v_min_i32_e32 v40, v78, v40
	v_max_i32_e32 v78, v16, v79
	v_min_i32_e32 v16, v16, v79
	v_max_i32_e32 v8, v11, v5
	v_min_i32_e32 v5, v11, v5
	v_max_i32_e32 v11, v12, v1
	v_min_i32_e32 v1, v12, v1
	v_max_i32_e32 v12, v15, v2
	v_min_i32_e32 v2, v15, v2
	v_max_i32_e32 v15, v13, v6
	v_min_i32_e32 v6, v13, v6
	v_max_i32_e32 v13, v14, v4
	v_min_i32_e32 v4, v14, v4
	v_max_i32_e32 v14, v3, v9
	v_min_i32_e32 v3, v3, v9
	v_max_i32_e32 v9, v88, v7
	v_min_i32_e32 v7, v88, v7
	v_max_i32_e32 v88, v0, v10
	v_min_i32_e32 v0, v0, v10
	v_max_i32_e32 v35, v33, v31
	v_min_i32_e32 v31, v33, v31
	v_max_i32_e32 v33, v36, v38
	v_min_i32_e32 v36, v36, v38
	v_max_i32_e32 v38, v37, v34
	v_min_i32_e32 v34, v37, v34
	v_max_i32_e32 v37, v39, v42
	v_min_i32_e32 v39, v39, v42
	v_max_i32_e32 v42, v30, v29
	v_min_i32_e32 v29, v30, v29
	v_max_i32_e32 v30, v26, v28
	v_min_i32_e32 v26, v26, v28
	v_max_i32_e32 v28, v25, v32
	v_min_i32_e32 v25, v25, v32
	v_max_i32_e32 v32, v27, v24
	v_min_i32_e32 v24, v27, v24
	v_max_i32_e32 v65, v63, v61
	v_min_i32_e32 v61, v63, v61
	v_max_i32_e32 v63, v66, v68
	v_min_i32_e32 v66, v66, v68
	v_max_i32_e32 v68, v67, v64
	v_min_i32_e32 v64, v67, v64
	v_max_i32_e32 v67, v69, v70
	v_min_i32_e32 v69, v69, v70
	v_max_i32_e32 v70, v60, v59
	v_min_i32_e32 v59, v60, v59
	v_max_i32_e32 v60, v56, v58
	v_min_i32_e32 v56, v56, v58
	v_max_i32_e32 v58, v55, v62
	v_min_i32_e32 v55, v55, v62
	v_max_i32_e32 v62, v57, v51
	v_min_i32_e32 v51, v57, v51
	v_max_i32_e32 v79, v52, v23
	v_min_i32_e32 v23, v52, v23
	v_max_i32_e32 v52, v80, v41
	v_min_i32_e32 v41, v80, v41
	v_max_i32_e32 v80, v44, v53
	v_min_i32_e32 v44, v44, v53
	v_max_i32_e32 v53, v54, v78
	v_min_i32_e32 v54, v54, v78
	v_max_i32_e32 v78, v21, v20
	v_min_i32_e32 v20, v21, v20
	v_max_i32_e32 v21, v17, v19
	v_min_i32_e32 v17, v17, v19
	v_max_i32_e32 v19, v18, v40
	v_min_i32_e32 v18, v18, v40
	v_max_i32_e32 v40, v22, v16
	v_min_i32_e32 v16, v22, v16
	v_max_i32_e32 v10, v8, v13
	v_min_i32_e32 v8, v8, v13
	v_max_i32_e32 v13, v11, v14
	v_min_i32_e32 v11, v11, v14
	v_max_i32_e32 v14, v12, v9
	v_min_i32_e32 v9, v12, v9
	v_max_i32_e32 v12, v15, v88
	v_min_i32_e32 v15, v15, v88
	v_max_i32_e32 v88, v5, v4
	v_min_i32_e32 v4, v5, v4
	v_max_i32_e32 v5, v1, v3
	v_min_i32_e32 v1, v1, v3
	v_max_i32_e32 v3, v2, v7
	v_min_i32_e32 v2, v2, v7
	v_max_i32_e32 v7, v6, v0
	v_min_i32_e32 v0, v6, v0
	v_max_i32_e32 v27, v35, v38
	v_min_i32_e32 v35, v35, v38
	v_max_i32_e32 v38, v33, v37
	v_min_i32_e32 v33, v33, v37
	v_max_i32_e32 v37, v31, v34
	v_min_i32_e32 v31, v31, v34
	v_max_i32_e32 v34, v36, v39
	v_min_i32_e32 v36, v36, v39
	v_max_i32_e32 v39, v42, v28
	v_min_i32_e32 v28, v42, v28
	v_max_i32_e32 v42, v30, v32
	v_min_i32_e32 v30, v30, v32
	v_max_i32_e32 v32, v29, v25
	v_min_i32_e32 v25, v29, v25
	v_max_i32_e32 v29, v26, v24
	v_min_i32_e32 v24, v26, v24
	v_max_i32_e32 v57, v65, v68
	v_min_i32_e32 v65, v65, v68
	v_max_i32_e32 v68, v63, v67
	v_min_i32_e32 v63, v63, v67
	v_max_i32_e32 v67, v61, v64
	v_min_i32_e32 v61, v61, v64
	v_max_i32_e32 v64, v66, v69
	v_min_i32_e32 v66, v66, v69
	v_max_i32_e32 v69, v70, v58
	v_min_i32_e32 v58, v70, v58
	v_max_i32_e32 v70, v60, v62
	v_min_i32_e32 v60, v60, v62
	v_max_i32_e32 v62, v59, v55
	v_min_i32_e32 v55, v59, v55
	v_max_i32_e32 v59, v56, v51
	v_min_i32_e32 v51, v56, v51
	v_max_i32_e32 v22, v79, v80
	v_min_i32_e32 v79, v79, v80
	v_max_i32_e32 v80, v52, v53
	v_min_i32_e32 v52, v52, v53
	v_max_i32_e32 v53, v23, v44
	v_min_i32_e32 v23, v23, v44
	v_max_i32_e32 v44, v41, v54
	v_min_i32_e32 v41, v41, v54
	v_max_i32_e32 v54, v78, v19
	v_min_i32_e32 v19, v78, v19
	v_max_i32_e32 v78, v21, v40
	v_min_i32_e32 v21, v21, v40
	v_max_i32_e32 v40, v20, v18
	v_min_i32_e32 v18, v20, v18
	v_max_i32_e32 v20, v17, v16
	v_min_i32_e32 v16, v17, v16
	v_max_i32_e32 v6, v10, v14
	v_min_i32_e32 v10, v10, v14
	v_max_i32_e32 v14, v13, v12
	v_min_i32_e32 v12, v13, v12
	v_max_i32_e32 v13, v8, v9
	v_min_i32_e32 v8, v8, v9
	v_max_i32_e32 v9, v11, v15
	v_min_i32_e32 v11, v11, v15
	v_max_i32_e32 v15, v88, v3
	v_min_i32_e32 v3, v88, v3
	v_max_i32_e32 v88, v5, v7
	v_min_i32_e32 v5, v5, v7
	v_max_i32_e32 v7, v4, v2
	v_min_i32_e32 v2, v4, v2
	v_max_i32_e32 v4, v1, v0
	v_min_i32_e32 v0, v1, v0
	v_min_i32_e32 v26, v27, v38
	v_min_i32_e32 v43, v35, v33
	v_min_i32_e32 v45, v37, v34
	v_min_i32_e32 v46, v31, v36
	v_min_i32_e32 v47, v39, v42
	v_min_i32_e32 v48, v28, v30
	v_min_i32_e32 v49, v32, v29
	v_min_i32_e32 v50, v25, v24
	v_min_i32_e32 v56, v57, v68
	v_min_i32_e32 v71, v65, v63
	v_min_i32_e32 v72, v67, v64
	v_min_i32_e32 v73, v61, v66
	v_min_i32_e32 v74, v69, v70
	v_min_i32_e32 v75, v58, v60
	v_min_i32_e32 v76, v62, v59
	v_min_i32_e32 v77, v55, v51
	v_min_i32_e32 v17, v22, v80
	v_min_i32_e32 v81, v79, v52
	v_min_i32_e32 v82, v53, v44
	v_min_i32_e32 v83, v23, v41
	v_min_i32_e32 v84, v54, v78
	v_min_i32_e32 v85, v19, v21
	v_min_i32_e32 v86, v40, v20
	v_min_i32_e32 v87, v18, v16
	v_min_i32_e32 v1, v6, v14
	v_min_i32_e32 v89, v10, v12
	v_min_i32_e32 v90, v13, v9
	v_min_i32_e32 v91, v8, v11
	v_min_i32_e32 v92, v15, v88
	v_min_i32_e32 v93, v3, v5
	v_min_i32_e32 v94, v7, v4
	v_min_i32_e32 v95, v2, v0
	v_max3_i32 v27, v27, v38, v77
	v_max3_i32 v26, v26, v55, v51
	v_max3_i32 v33, v35, v33, v76
	v_max3_i32 v35, v43, v62, v59
	v_max3_i32 v34, v37, v34, v75
	v_max3_i32 v37, v45, v58, v60
	v_max3_i32 v31, v31, v36, v74
	v_max3_i32 v36, v46, v69, v70
	v_max3_i32 v38, v39, v42, v73
	v_max3_i32 v39, v47, v61, v66
	v_max3_i32 v28, v28, v30, v72
	v_max3_i32 v30, v48, v67, v64
	v_max3_i32 v29, v32, v29, v71
	v_max3_i32 v32, v49, v65, v63
	v_max3_i32 v24, v25, v24, v56
	v_max3_i32 v25, v50, v57, v68
	v_max3_i32 v22, v22, v80, v95
	v_max3_i32 v0, v17, v2, v0
	v_max3_i32 v2, v79, v52, v94
	v_max3_i32 v4, v81, v7, v4
	v_max3_i32 v7, v53, v44, v93
	v_max3_i32 v3, v82, v3, v5
	v_max3_i32 v5, v23, v41, v92
	v_max3_i32 v15, v83, v15, v88
	v_max3_i32 v17, v54, v78, v91
	v_max3_i32 v8, v84, v8, v11
	v_max3_i32 v11, v19, v21, v90
	v_max3_i32 v9, v85, v13, v9
	v_max3_i32 v13, v40, v20, v89
	v_max3_i32 v10, v86, v10, v12
	v_max3_i32 v1, v18, v16, v1
	v_max3_i32 v6, v87, v6, v14
	v_max_i32_e32 v42, v27, v38
	v_min_i32_e32 v27, v27, v38
	v_max_i32_e32 v38, v26, v39
	v_min_i32_e32 v26, v26, v39
	v_max_i32_e32 v39, v33, v28
	v_min_i32_e32 v28, v33, v28
	v_max_i32_e32 v33, v35, v30
	v_min_i32_e32 v30, v35, v30
	v_max_i32_e32 v35, v34, v29
	v_min_i32_e32 v29, v34, v29
	v_max_i32_e32 v34, v37, v32
	v_min_i32_e32 v32, v37, v32
	v_max_i32_e32 v37, v31, v24
	v_min_i32_e32 v24, v31, v24
	v_max_i32_e32 v31, v36, v25
	v_min_i32_e32 v25, v36, v25
	v_max_i32_e32 v12, v22, v17
	v_min_i32_e32 v14, v22, v17
	v_max_i32_e32 v16, v0, v8
	v_min_i32_e32 v0, v0, v8
	v_max_i32_e32 v8, v2, v11
	v_min_i32_e32 v2, v2, v11
	v_max_i32_e32 v11, v4, v9
	v_min_i32_e32 v4, v4, v9
	v_max_i32_e32 v9, v7, v13
	v_min_i32_e32 v7, v7, v13
	v_max_i32_e32 v13, v3, v10
	v_min_i32_e32 v3, v3, v10
	v_max_i32_e32 v10, v5, v1
	v_min_i32_e32 v1, v5, v1
	v_max_i32_e32 v5, v15, v6
	v_min_i32_e32 v6, v15, v6
	v_max_i32_e32 v36, v42, v35
	v_min_i32_e32 v35, v42, v35
	v_max_i32_e32 v42, v38, v34
	v_min_i32_e32 v34, v38, v34
	v_max_i32_e32 v38, v39, v37
	v_min_i32_e32 v37, v39, v37
	v_max_i32_e32 v39, v33, v31
	v_min_i32_e32 v31, v33, v31
	v_max_i32_e32 v33, v27, v29
	v_min_i32_e32 v27, v27, v29
	v_max_i32_e32 v29, v26, v32
	v_min_i32_e32 v26, v26, v32
	v_max_i32_e32 v32, v28, v24
	v_min_i32_e32 v24, v28, v24
	v_max_i32_e32 v28, v30, v25
	v_min_i32_e32 v25, v30, v25
	v_max_i32_e32 v15, v12, v9
	v_min_i32_e32 v9, v12, v9
	v_max_i32_e32 v12, v16, v13
	v_min_i32_e32 v13, v16, v13
	v_max_i32_e32 v16, v8, v10
	v_min_i32_e32 v8, v8, v10
	v_max_i32_e32 v10, v11, v5
	v_min_i32_e32 v5, v11, v5
	v_max_i32_e32 v11, v14, v7
	v_min_i32_e32 v7, v14, v7
	v_max_i32_e32 v14, v0, v3
	v_min_i32_e32 v0, v0, v3
	v_max_i32_e32 v3, v2, v1
	v_min_i32_e32 v1, v2, v1
	v_max_i32_e32 v2, v4, v6
	v_min_i32_e32 v4, v4, v6
	v_max_i32_e32 v30, v36, v38
	v_min_i32_e32 v36, v36, v38
	v_max_i32_e32 v38, v42, v39
	v_min_i32_e32 v39, v42, v39
	v_max_i32_e32 v42, v35, v37
	v_min_i32_e32 v35, v35, v37
	v_max_i32_e32 v37, v34, v31
	v_min_i32_e32 v31, v34, v31
	v_max_i32_e32 v34, v33, v32
	v_min_i32_e32 v32, v33, v32
	v_max_i32_e32 v33, v29, v28
	v_min_i32_e32 v28, v29, v28
	v_max_i32_e32 v29, v27, v24
	v_min_i32_e32 v24, v27, v24
	v_max_i32_e32 v27, v26, v25
	v_min_i32_e32 v25, v26, v25
	v_max_i32_e32 v6, v15, v16
	v_min_i32_e32 v15, v15, v16
	v_max_i32_e32 v16, v12, v10
	v_min_i32_e32 v10, v12, v10
	v_max_i32_e32 v12, v9, v8
	v_min_i32_e32 v8, v9, v8
	v_max_i32_e32 v9, v13, v5
	v_min_i32_e32 v5, v13, v5
	v_max_i32_e32 v13, v11, v3
	v_min_i32_e32 v3, v11, v3
	v_max_i32_e32 v11, v14, v2
	v_min_i32_e32 v2, v14, v2
	v_max_i32_e32 v14, v7, v1
	v_min_i32_e32 v1, v7, v1
	v_max_i32_e32 v7, v0, v4
	v_min_i32_e32 v0, v0, v4
	v_min_i32_e32 v26, v30, v38
	v_min_i32_e32 v43, v36, v39
	v_min_i32_e32 v45, v42, v37
	v_min_i32_e32 v46, v35, v31
	v_min_i32_e32 v47, v34, v33
	v_min_i32_e32 v48, v32, v28
	v_min_i32_e32 v49, v29, v27
	v_min_i32_e32 v50, v24, v25
	v_min_i32_e32 v4, v6, v16
	v_min_i32_e32 v17, v15, v10
	v_min_i32_e32 v18, v12, v9
	v_min_i32_e32 v19, v8, v5
	v_min_i32_e32 v20, v13, v11
	v_min_i32_e32 v21, v3, v2
	v_min_i32_e32 v22, v14, v7
	v_min_i32_e32 v23, v1, v0
	v_max3_i32 v23, v30, v38, v23
	v_max3_i32 v0, v26, v1, v0
	v_max3_i32 v1, v36, v39, v22
	v_max3_i32 v7, v43, v14, v7
	v_max3_i32 v14, v42, v37, v21
	v_max3_i32 v2, v45, v3, v2
	v_max3_i32 v3, v35, v31, v20
	v_max3_i32 v11, v46, v13, v11
	v_max3_i32 v13, v34, v33, v19
	v_max3_i32 v5, v47, v8, v5
	v_max3_i32 v8, v32, v28, v18
	v_max3_i32 v9, v48, v12, v9
	v_max3_i32 v12, v29, v27, v17
	v_max3_i32 v10, v49, v15, v10
	v_max3_i32 v4, v24, v25, v4
	v_max3_i32 v6, v50, v6, v16
	v_max_i32_e32 v15, v23, v13
	v_min_i32_e32 v13, v23, v13
	v_max_i32_e32 v16, v0, v5
	v_min_i32_e32 v0, v0, v5
	v_max_i32_e32 v5, v1, v8
	v_min_i32_e32 v1, v1, v8
	v_max_i32_e32 v8, v7, v9
	v_min_i32_e32 v7, v7, v9
	v_max_i32_e32 v9, v14, v12
	v_min_i32_e32 v12, v14, v12
	v_max_i32_e32 v14, v2, v10
	v_min_i32_e32 v2, v2, v10
	v_max_i32_e32 v10, v3, v4
	v_min_i32_e32 v3, v3, v4
	v_max_i32_e32 v4, v11, v6
	v_min_i32_e32 v6, v11, v6
	v_max_i32_e32 v11, v15, v9
	v_min_i32_e32 v9, v15, v9
	v_max_i32_e32 v15, v16, v14
	v_min_i32_e32 v14, v16, v14
	v_max_i32_e32 v16, v5, v10
	v_min_i32_e32 v5, v5, v10
	v_max_i32_e32 v10, v8, v4
	v_min_i32_e32 v4, v8, v4
	v_max_i32_e32 v8, v13, v12
	v_min_i32_e32 v12, v13, v12
	v_max_i32_e32 v13, v0, v2
	v_min_i32_e32 v0, v0, v2
	v_max_i32_e32 v2, v1, v3
	v_min_i32_e32 v1, v1, v3
	v_max_i32_e32 v3, v7, v6
	v_min_i32_e32 v6, v7, v6
	v_max_i32_e32 v7, v11, v16
	v_min_i32_e32 v11, v11, v16
	v_max_i32_e32 v16, v15, v10
	v_min_i32_e32 v10, v15, v10
	v_max_i32_e32 v15, v9, v5
	v_min_i32_e32 v5, v9, v5
	v_max_i32_e32 v9, v14, v4
	v_min_i32_e32 v4, v14, v4
	v_max_i32_e32 v14, v8, v2
	v_min_i32_e32 v2, v8, v2
	v_max_i32_e32 v8, v13, v3
	v_min_i32_e32 v3, v13, v3
	v_max_i32_e32 v13, v12, v1
	v_min_i32_e32 v1, v12, v1
	v_max_i32_e32 v12, v0, v6
	v_min_i32_e32 v0, v0, v6
	v_max_i32_e32 v6, v7, v16
	v_min_i32_e32 v7, v7, v16
	v_max_i32_e32 v16, v11, v10
	v_min_i32_e32 v10, v11, v10
	v_max_i32_e32 v11, v15, v9
	v_min_i32_e32 v9, v15, v9
	v_max_i32_e32 v15, v5, v4
	v_min_i32_e32 v4, v5, v4
	v_max_i32_e32 v5, v14, v8
	v_min_i32_e32 v8, v14, v8
	v_max_i32_e32 v14, v2, v3
	v_min_i32_e32 v2, v2, v3
	v_max_i32_e32 v3, v13, v12
	v_min_i32_e32 v13, v13, v12
	v_and_b32_e32 v12, 64, v188
	v_max_i32_e32 v17, v1, v0
	v_min_i32_e32 v0, v1, v0
	v_xor_b32_e32 v1, 32, v188
	v_add_u32_e32 v12, 64, v12
	v_cmp_lt_i32_e32 vcc, v1, v12
	s_barrier
	s_nop 0
	v_cndmask_b32_e32 v1, v188, v1, vcc
	v_lshlrev_b32_e32 v12, 2, v1
	ds_bpermute_b32 v1, v12, v6
	ds_bpermute_b32 v18, v12, v7
	ds_bpermute_b32 v19, v12, v16
	ds_bpermute_b32 v20, v12, v10
	ds_bpermute_b32 v21, v12, v11
	ds_bpermute_b32 v22, v12, v9
	ds_bpermute_b32 v23, v12, v15
	ds_bpermute_b32 v24, v12, v4
	ds_bpermute_b32 v25, v12, v5
	ds_bpermute_b32 v26, v12, v8
	ds_bpermute_b32 v27, v12, v14
	ds_bpermute_b32 v28, v12, v0
	ds_bpermute_b32 v29, v12, v17
	ds_bpermute_b32 v30, v12, v13
	ds_bpermute_b32 v31, v12, v3
	ds_bpermute_b32 v32, v12, v2
	s_waitcnt lgkmcnt(4)
	v_max_i32_e32 v6, v6, v28
	s_waitcnt lgkmcnt(3)
	v_max_i32_e32 v7, v7, v29
	s_waitcnt lgkmcnt(2)
	v_max_i32_e32 v16, v16, v30
	s_waitcnt lgkmcnt(1)
	v_max_i32_e32 v10, v10, v31
	s_waitcnt lgkmcnt(0)
	v_max_i32_e32 v11, v11, v32
	v_max_i32_e32 v9, v9, v27
	v_max_i32_e32 v15, v15, v26
	v_max_i32_e32 v4, v4, v25
	v_max_i32_e32 v5, v5, v24
	v_max_i32_e32 v8, v8, v23
	v_max_i32_e32 v14, v14, v22
	v_max_i32_e32 v2, v2, v21
	v_max_i32_e32 v3, v3, v20
	v_max_i32_e32 v13, v13, v19
	v_max_i32_e32 v17, v17, v18
	v_max_i32_e32 v0, v0, v1
	v_max_i32_e32 v1, v6, v5
	v_min_i32_e32 v5, v6, v5
	v_max_i32_e32 v6, v7, v8
	v_min_i32_e32 v7, v7, v8
	v_max_i32_e32 v8, v16, v14
	v_min_i32_e32 v14, v16, v14
	v_max_i32_e32 v16, v10, v2
	v_min_i32_e32 v2, v10, v2
	v_max_i32_e32 v10, v11, v3
	v_min_i32_e32 v3, v11, v3
	v_max_i32_e32 v11, v9, v13
	v_min_i32_e32 v9, v9, v13
	v_max_i32_e32 v13, v15, v17
	v_min_i32_e32 v15, v15, v17
	v_max_i32_e32 v17, v4, v0
	v_min_i32_e32 v0, v4, v0
	v_max_i32_e32 v4, v1, v10
	v_min_i32_e32 v1, v1, v10
	v_max_i32_e32 v10, v6, v11
	v_min_i32_e32 v6, v6, v11
	v_max_i32_e32 v11, v8, v13
	v_min_i32_e32 v8, v8, v13
	v_max_i32_e32 v13, v16, v17
	v_min_i32_e32 v16, v16, v17
	v_max_i32_e32 v17, v5, v3
	v_min_i32_e32 v3, v5, v3
	v_max_i32_e32 v5, v7, v9
	v_min_i32_e32 v7, v7, v9
	v_max_i32_e32 v9, v14, v15
	v_min_i32_e32 v14, v14, v15
	v_max_i32_e32 v15, v2, v0
	v_min_i32_e32 v0, v2, v0
	v_max_i32_e32 v2, v4, v11
	v_min_i32_e32 v4, v4, v11
	v_max_i32_e32 v11, v10, v13
	v_min_i32_e32 v10, v10, v13
	v_max_i32_e32 v13, v1, v8
	v_min_i32_e32 v1, v1, v8
	v_max_i32_e32 v8, v6, v16
	v_min_i32_e32 v6, v6, v16
	v_max_i32_e32 v16, v17, v9
	v_min_i32_e32 v9, v17, v9
	v_max_i32_e32 v17, v5, v15
	v_min_i32_e32 v5, v5, v15
	v_max_i32_e32 v15, v3, v14
	v_min_i32_e32 v3, v3, v14
	v_max_i32_e32 v14, v7, v0
	v_min_i32_e32 v0, v7, v0
	v_max_i32_e32 v7, v2, v11
	v_min_i32_e32 v2, v2, v11
	v_max_i32_e32 v25, v3, v0
	v_min_i32_e32 v26, v3, v0
	v_ashrrev_i32_e32 v0, 31, v7
	v_max_i32_e32 v11, v4, v10
	v_bitop3_b32 v20, v0, v7, s11 bitop3:0x6c
	v_ashrrev_i32_e32 v0, 31, v2
	v_min_i32_e32 v4, v4, v10
	v_bitop3_b32 v19, v0, v2, s11 bitop3:0x6c
	v_ashrrev_i32_e32 v0, 31, v11
	v_max_i32_e32 v10, v13, v8
	v_bitop3_b32 v18, v0, v11, s11 bitop3:0x6c
	v_ashrrev_i32_e32 v0, 31, v4
	v_min_i32_e32 v8, v13, v8
	v_max_i32_e32 v13, v1, v6
	v_min_i32_e32 v1, v1, v6
	v_max_i32_e32 v6, v16, v17
	v_min_i32_e32 v21, v16, v17
	v_bitop3_b32 v17, v0, v4, s11 bitop3:0x6c
	v_ashrrev_i32_e32 v0, 31, v10
	v_bitop3_b32 v16, v0, v10, s11 bitop3:0x6c
	v_ashrrev_i32_e32 v0, 31, v8
	v_max_i32_e32 v23, v15, v14
	v_min_i32_e32 v24, v15, v14
	v_bitop3_b32 v15, v0, v8, s11 bitop3:0x6c
	v_ashrrev_i32_e32 v0, 31, v13
	v_bitop3_b32 v14, v0, v13, s11 bitop3:0x6c
	v_ashrrev_i32_e32 v0, 31, v1
	v_bitop3_b32 v13, v0, v1, s11 bitop3:0x6c
	v_ashrrev_i32_e32 v0, 31, v6
	v_ashrrev_i32_e32 v1, 31, v21
	v_max_i32_e32 v22, v9, v5
	v_min_i32_e32 v9, v9, v5
	v_and_b32_e32 v0, 0x7fffffff, v0
	v_and_b32_e32 v2, 0x7fffffff, v1
	v_xor_b32_e32 v1, v0, v6
	v_xor_b32_e32 v0, v2, v21
	v_ashrrev_i32_e32 v2, 31, v22
	v_ashrrev_i32_e32 v3, 31, v9
	v_and_b32_e32 v2, 0x7fffffff, v2
	v_and_b32_e32 v3, 0x7fffffff, v3
	v_xor_b32_e32 v5, v2, v22
	v_xor_b32_e32 v4, v3, v9
	v_ashrrev_i32_e32 v2, 31, v23
	v_ashrrev_i32_e32 v3, 31, v24
	v_and_b32_e32 v2, 0x7fffffff, v2
	v_and_b32_e32 v6, 0x7fffffff, v3
	v_xor_b32_e32 v3, v2, v23
	v_xor_b32_e32 v2, v6, v24
	v_ashrrev_i32_e32 v6, 31, v25
	v_bitop3_b32 v11, v6, v25, s11 bitop3:0x6c
	v_ashrrev_i32_e32 v6, 31, v26
	v_bitop3_b32 v10, v6, v26, s11 bitop3:0x6c
	s_and_b64 vcc, exec, s[56:57]
	s_cbranch_vccnz .LBB0_1001
	v_mov_b32_e32 v221, v20
	v_mov_b32_e32 v222, v19
	v_mov_b32_e32 v223, v18
	v_mov_b32_e32 v224, v17
	v_mov_b32_e32 v225, v16
	v_mov_b32_e32 v226, v15
	v_mov_b32_e32 v227, v14
	v_mov_b32_e32 v228, v13
	v_mov_b32_e32 v229, v11
	v_mov_b32_e32 v230, v10
	v_mov_b64_e32 v[154:155], v[2:3]
	v_mov_b64_e32 v[156:157], v[4:5]
	v_mov_b64_e32 v[158:159], v[0:1]
	s_branch .LBB0_1003
